# attention K tile LDS swizzle widened to 4 bits (row&15) on DMA source + K-fragment reads (bank-conflict fix), on top of v2 resid epilogues
# speedup vs baseline: 1.0085x; 1.0085x over previous
.LBB0_1307:
	v_mov_b32_e32 v60, v0
	s_and_b32 s75, s4, 7
	v_readfirstlane_b32 s2, v60
	s_ashr_i32 s22, s2, 6
	s_and_b32 s2, s2, 0x3fffffc0
	s_lshl_b32 s2, s2, 2
	s_add_i32 s78, s2, 0
	s_lshl_b32 s2, s22, 10
	s_ashr_i32 s23, s2, 8
	s_and_b32 s24, s23, 0x1ffff0
	s_lshr_b32 s23, s23, 1
	s_and_b32 s23, s23, 4
	s_add_i32 s33, s2, 0x2000
	s_or_b32 s23, s24, s23
	s_ashr_i32 s24, s33, 8
	s_ashr_i32 s10, s4, 7
	s_xor_b32 s12, s75, 15
	s_and_b32 s25, s24, 0x1ffff0
	s_lshr_b32 s24, s24, 1
	s_bfe_u32 s3, s4, 0x40003
	s_ashr_i32 s11, s10, 31
	s_lshl_b32 s80, s12, 2
	s_and_b32 s24, s24, 4
	s_lshl_b32 s56, s3, 8
	s_lshl_b64 s[62:63], s[10:11], 12
	s_lshl_b32 s82, s22, 5
	s_add_i32 s78, s78, 0x14000
	s_or_b32 s38, s25, s24
	s_lshl_b32 s39, s12, 8
	s_add_i32 s81, s80, 4
	s_lshl_b32 s12, s3, 7
	s_lshl_b64 s[24:25], s[10:11], 24
	s_add_u32 s40, s9, s24
	s_addc_u32 s41, s58, s25
	s_lshl_b32 s79, s22, 12
	s_lshl_b64 s[60:61], s[10:11], 19
	s_add_i32 s10, s79, 0
	s_add_i32 s10, s10, 0x14800
	s_or_b32 s11, s62, s39
	s_ashr_i32 s22, s82, 31
	s_add_u32 s76, s11, s82
	v_and_b32_e32 v195, 31, v60
	s_addc_u32 s77, s63, s22
	v_or_b32_e32 v18, s76, v195
	v_mov_b32_e32 v19, s77
	v_lshlrev_b64 v[2:3], 11, v[18:19]
	v_bfe_u32 v196, v60, 5, 1
	v_lshl_add_u64 v[2:3], s[18:19], 0, v[2:3]
	v_lshlrev_b32_e32 v162, 4, v196
	v_mov_b32_e32 v163, v167
	v_lshl_add_u64 v[2:3], v[2:3], 0, s[12:13]
	v_lshl_add_u64 v[14:15], v[2:3], 0, v[162:163]
	global_load_dwordx4 v[2:5], v[14:15], off
	global_load_dwordx4 v[6:9], v[14:15], off offset:32
	global_load_dwordx4 v[10:13], v[14:15], off offset:64
	s_nop 0
	global_load_dwordx4 v[14:17], v[14:15], off offset:96
	v_lshlrev_b64 v[18:19], 12, v[18:19]
	s_mov_b32 s57, s13
	v_lshl_add_u64 v[18:19], s[14:15], 0, v[18:19]
	v_lshl_add_u64 v[18:19], v[18:19], 0, s[56:57]
	v_lshl_add_u64 v[18:19], v[18:19], 0, v[162:163]
	global_load_dwordx4 v[158:161], v[18:19], off
	global_load_dwordx4 v[154:157], v[18:19], off offset:32
	global_load_dwordx4 v[150:153], v[18:19], off offset:64
	global_load_dwordx4 v[146:149], v[18:19], off offset:96
	global_load_dwordx4 v[142:145], v[18:19], off offset:128
	global_load_dwordx4 v[138:141], v[18:19], off offset:160
	global_load_dwordx4 v[134:137], v[18:19], off offset:192
	global_load_dwordx4 v[130:133], v[18:19], off offset:224
	v_and_b32_e32 v194, 63, v60
	v_lshlrev_b32_e32 v99, 4, v194
	v_bfe_u32 v21, v60, 2, 2
	v_lshrrev_b32_e32 v22, 1, v60
	v_and_or_b32 v21, v22, 8, v21
	v_or_b32_e32 v22, s2, v99
	v_ashrrev_i32_e32 v23, 8, v22
	v_and_b32_e32 v20, 0xf0, v99
	v_lshlrev_b32_e32 v24, 4, v23
	s_movk_i32 s42, 0x70
	v_and_b32_e32 v24, 0xf0, v24
	v_xor_b32_e32 v24, v24, v20
	v_lshrrev_b32_e32 v24, 1, v24
	v_lshlrev_b32_e32 v61, 3, v194
	v_lshl_or_b32 v166, v23, 11, v24
	v_or_b32_e32 v23, s23, v21
	v_lshrrev_b32_e32 v24, 4, v22
	s_add_i32 s82, s82, s39
	v_and_b32_e32 v98, 24, v61
	v_and_b32_e32 v24, 0x60, v24
	v_lshlrev_b32_e32 v23, 11, v23
	s_add_u32 s11, s5, s24
	v_or3_b32 v23, v23, v24, v98
	v_or_b32_e32 v24, s33, v99
	s_addc_u32 s33, s6, s25
	s_add_u32 s22, s40, s56
	s_addc_u32 s23, s41, 0
	s_lshl_b32 s57, s3, 6
	v_ashrrev_i32_e32 v25, 8, v24
	s_add_u32 s68, s11, s56
	v_lshlrev_b32_e32 v26, 4, v25
	v_or_b32_e32 v21, s38, v21
	v_lshrrev_b32_e32 v24, 4, v24
	s_addc_u32 s69, s33, 0
	v_and_b32_e32 v26, 0xf0, v26
	v_xor_b32_e32 v20, v26, v20
	v_and_b32_e32 v24, 0x60, v24
	v_lshlrev_b32_e32 v21, 11, v21
	s_add_u32 s66, s7, s60
	v_lshrrev_b32_e32 v20, 1, v20
	v_or3_b32 v164, v21, v24, v98
	v_ashrrev_i32_e32 v21, 7, v22
	s_addc_u32 s67, s8, s61
	s_add_i32 s83, s2, 0
	v_lshl_or_b32 v20, v25, 11, v20
	v_xor_b32_e32 v22, v21, v60
	v_lshlrev_b32_e32 v18, 6, v21
	v_add_u32_e32 v200, s10, v99
	v_lshlrev_b64 v[50:51], 1, v[166:167]
	s_add_i32 s92, s83, 0x8000
	v_mov_b32_e32 v21, v167
	s_waitcnt vmcnt(0)
	ds_write_b128 v200, v[2:5]
	ds_write_b128 v200, v[6:9] offset:1024
	ds_write_b128 v200, v[10:13] offset:2048
	ds_write_b128 v200, v[14:17] offset:3072
	v_lshl_add_u64 v[4:5], s[68:69], 0, v[50:51]
	s_mov_b32 m0, s92
	v_lshlrev_b64 v[52:53], 1, v[20:21]
	s_add_i32 s93, s83, 0xa000
	global_load_lds_dwordx4 v[4:5], off
	v_lshl_add_u64 v[4:5], s[68:69], 0, v[52:53]
	s_mov_b32 m0, s93
	s_add_i32 s11, 0, 0x10000
	global_load_lds_dwordx4 v[4:5], off
	s_add_i32 m0, s11, s2
	v_lshlrev_b32_e32 v22, 3, v22
	s_add_u32 s70, s68, 0x40000
	v_and_or_b32 v2, v22, 56, v18
	v_mov_b32_e32 v3, v167
	s_addc_u32 s71, s69, 0
	v_lshlrev_b64 v[54:55], 1, v[2:3]
	s_add_u32 s72, s66, 0x2000
	v_lshl_add_u64 v[2:3], s[66:67], 0, v[54:55]
	s_addc_u32 s73, s67, 0
	s_add_i32 s94, s83, 0xc000
	global_load_lds_dwordx4 v[2:3], off
	v_lshl_add_u64 v[2:3], s[70:71], 0, v[50:51]
	s_mov_b32 m0, s94
	s_add_i32 s95, s83, 0xe000
	s_waitcnt vmcnt(0) lgkmcnt(0)
	s_waitcnt vmcnt(0) lgkmcnt(0)
	s_barrier
	global_load_lds_dwordx4 v[2:3], off
	v_lshl_add_u64 v[2:3], s[70:71], 0, v[52:53]
	s_mov_b32 m0, s95
	s_add_i32 s10, 0, 0x12000
	v_mov_b32_e32 v166, v23
	global_load_lds_dwordx4 v[2:3], off
	v_lshl_add_u64 v[2:3], s[72:73], 0, v[54:55]
	s_add_i32 m0, s10, s2
	v_lshlrev_b64 v[56:57], 1, v[166:167]
	v_mov_b32_e32 v165, v167
	global_load_lds_dwordx4 v[2:3], off
	v_lshl_add_u64 v[2:3], s[22:23], 0, v[56:57]
	s_mov_b32 m0, s83
	v_lshlrev_b64 v[58:59], 1, v[164:165]
	s_add_i32 s96, s83, 0x2000
	v_lshlrev_b32_e32 v163, 4, v60
	global_load_lds_dwordx4 v[2:3], off
	v_lshl_add_u64 v[2:3], s[22:23], 0, v[58:59]
	s_mov_b32 m0, s96
	v_bitop3_b32 v201, v162, v163, s42 bitop3:0x78
	v_lshl_add_u32 v100, v195, 8, 0
	global_load_lds_dwordx4 v[2:3], off
	v_and_b32_e32 v253, 0x80, v163
	v_add3_u32 v38, v100, v201, v253
	v_xor_b32_e32 v250, 0x80, v38
	ds_read_b128 v[2:5], v38 offset:32768
	ds_read_b128 v[6:9], v250 offset:32768
	v_and_b32_e32 v14, 0x70, v163
	v_bitop3_b32 v202, v162, v14, 32 bitop3:0x36
	v_add3_u32 v86, v100, v202, v253
	v_xor_b32_e32 v251, 0x80, v86
	s_waitcnt lgkmcnt(0)
	v_mfma_f32_32x32x16_bf16 v[18:33], v[2:5], v[158:161], 0
	ds_read_b128 v[2:5], v86 offset:32768
	ds_read_b128 v[10:13], v251 offset:32768
	v_bitop3_b32 v203, v162, v14, 64 bitop3:0x36
	v_add3_u32 v90, v100, v203, v253
	v_xor_b32_e32 v252, 0x80, v90
	s_movk_i32 s2, 0x60
	v_bitop3_b32 v204, v162, v14, s2 bitop3:0x36
	ds_read_b128 v[14:17], v252 offset:32768
	s_waitcnt lgkmcnt(0)
	v_mfma_f32_32x32x16_bf16 v[18:33], v[2:5], v[154:157], v[18:33]
	ds_read_b128 v[2:5], v90 offset:32768
	v_add3_u32 v94, v100, v204, v253
	v_xor_b32_e32 v253, 0x80, v94
	v_lshlrev_b32_e32 v101, 7, v195
	s_movk_i32 s2, 0xc0
	s_mov_b32 s40, s13
	s_mov_b32 s41, s13
	s_mov_b32 s42, s13
	s_waitcnt lgkmcnt(0)
	v_mfma_f32_32x32x16_bf16 v[18:33], v[2:5], v[150:153], v[18:33]
	ds_read_b128 v[2:5], v94 offset:32768
	ds_read_b128 v[34:37], v253 offset:32768
	s_mov_b32 s43, s13
	s_mov_b32 s44, s13
	s_mov_b32 s45, s13
	s_mov_b32 s46, s13
	s_mov_b32 s47, s13
	s_mov_b32 s48, s13
	s_waitcnt lgkmcnt(0)
	v_mfma_f32_32x32x16_bf16 v[18:33], v[2:5], v[146:149], v[18:33]
	s_mov_b32 s49, s13
	s_mov_b32 s50, s13
	s_mov_b32 s51, s13
	s_mov_b32 s52, s13
	s_mov_b32 s53, s13
	s_mov_b32 s54, s13
	s_mov_b32 s55, s13
	v_mfma_f32_32x32x16_bf16 v[18:33], v[6:9], v[142:145], v[18:33]
	s_cmp_lg_u32 0, -1
	v_lshl_add_u64 v[174:175], s[60:61], 0, v[54:55]
	s_mov_b32 s97, 2
	v_add_u32_e32 v214, s10, v101
	v_cmp_gt_u32_e64 s[38:39], 32, v194
	v_lshl_add_u32 v197, v195, 2, s78
	v_mov_b32_e32 v215, 1.0
	v_mfma_f32_32x32x16_bf16 v[18:33], v[10:13], v[138:141], v[18:33]
	v_mov_b32_e32 v198, 0
	s_movk_i32 s33, 0x80
	v_mfma_f32_32x32x16_bf16 v[18:33], v[14:17], v[134:137], v[18:33]
	v_mfma_f32_32x32x16_bf16 v[18:33], v[34:37], v[130:133], v[18:33]
	v_add_u32_e32 v34, s11, v101
	v_add_u32_e32 v205, v34, v201
	ds_read_b128 v[2:5], v205
	ds_read_b128 v[6:9], v200
	ds_read_b128 v[10:13], v205 offset:4096
	ds_read_b128 v[14:17], v200 offset:1024
	v_add_u32_e32 v206, v34, v202
	v_add_u32_e32 v207, v34, v203
	v_add_u32_e32 v208, v34, v204
	s_waitcnt lgkmcnt(0)
	v_mfma_f32_32x32x16_bf16 v[18:33], v[2:5], v[6:9], v[18:33]
	ds_read_b128 v[2:5], v206
	ds_read_b128 v[62:65], v206 offset:4096
	s_waitcnt lgkmcnt(0)
	v_mfma_f32_32x32x16_bf16 v[18:33], v[2:5], v[14:17], v[18:33]
	ds_read_b128 v[2:5], v207
	ds_read_b128 v[66:69], v200 offset:2048
	ds_read_b128 v[70:73], v207 offset:4096
	ds_read_b128 v[74:77], v200 offset:3072
	s_waitcnt lgkmcnt(0)
	v_mfma_f32_32x32x16_bf16 v[18:33], v[2:5], v[66:69], v[18:33]
	ds_read_b128 v[2:5], v208
	ds_read_b128 v[78:81], v208 offset:4096
	s_waitcnt lgkmcnt(0)
	v_mfma_f32_32x32x16_bf16 v[18:33], v[2:5], v[74:77], v[18:33]
	ds_read_b128 v[2:5], v38 offset:40960
	ds_read_b128 v[82:85], v250 offset:40960
	s_waitcnt lgkmcnt(0)
	v_mfma_f32_32x32x16_bf16 v[34:49], v[2:5], v[158:161], 0
	ds_read_b128 v[2:5], v86 offset:40960
	ds_read_b128 v[86:89], v251 offset:40960
	s_waitcnt lgkmcnt(0)
	v_mfma_f32_32x32x16_bf16 v[34:49], v[2:5], v[154:157], v[34:49]
	ds_read_b128 v[2:5], v90 offset:40960
	ds_read_b128 v[90:93], v252 offset:40960
	s_waitcnt lgkmcnt(0)
	v_mfma_f32_32x32x16_bf16 v[34:49], v[2:5], v[150:153], v[34:49]
	ds_read_b128 v[2:5], v94 offset:40960
	ds_read_b128 v[94:97], v253 offset:40960
	s_waitcnt vmcnt(0) lgkmcnt(0)
	s_waitcnt vmcnt(0) lgkmcnt(0)
	s_barrier
	v_mfma_f32_32x32x16_bf16 v[34:49], v[2:5], v[146:149], v[34:49]
	v_lshlrev_b32_e32 v2, 1, v60
	v_and_b32_e32 v2, 32, v2
	v_and_or_b32 v2, v99, s2, v2
	v_and_b32_e32 v3, 0x100, v61
	v_or3_b32 v61, v2, v3, v98
	s_cselect_b32 s2, 0, 0
	s_or_b32 s24, s24, s56
	v_mfma_f32_32x32x16_bf16 v[34:49], v[82:85], v[142:145], v[34:49]
	v_add_u32_e32 v199, s2, v61
	v_lshl_add_u64 v[176:177], s[24:25], 0, v[50:51]
	v_lshl_add_u64 v[178:179], s[24:25], 0, v[52:53]
	v_lshl_add_u64 v[180:181], s[24:25], 0, v[56:57]
	v_lshl_add_u64 v[182:183], s[24:25], 0, v[58:59]
	v_mfma_f32_32x32x16_bf16 v[34:49], v[86:89], v[138:141], v[34:49]
	v_mfma_f32_32x32x16_bf16 v[34:49], v[90:93], v[134:137], v[34:49]
	v_mfma_f32_32x32x16_bf16 v[34:49], v[94:97], v[130:133], v[34:49]
	v_mfma_f32_32x32x16_bf16 v[34:49], v[10:13], v[6:9], v[34:49]
	v_mfma_f32_32x32x16_bf16 v[34:49], v[62:65], v[14:17], v[34:49]
	v_max_f32_e32 v62, v19, v19
	v_max_f32_e32 v63, v18, v18
	v_max_f32_e32 v62, v63, v62
	v_max3_f32 v62, v62, v20, v21
	v_max3_f32 v62, v62, v22, v23
	v_max3_f32 v62, v62, v24, v25
	v_max3_f32 v62, v62, v26, v27
	v_mfma_f32_32x32x16_bf16 v[34:49], v[70:73], v[66:69], v[34:49]
	v_max3_f32 v62, v62, v28, v29
	v_max3_f32 v62, v62, v30, v31
	v_max3_f32 v62, v62, v32, v33
	v_mov_b64_e32 v[2:3], s[40:41]
	v_mov_b64_e32 v[16:17], s[54:55]
	v_mov_b64_e32 v[4:5], s[42:43]
	v_mov_b64_e32 v[6:7], s[44:45]
	v_mfma_f32_32x32x16_bf16 v[34:49], v[78:81], v[74:77], v[34:49]
	v_mov_b64_e32 v[8:9], s[46:47]
	v_mov_b64_e32 v[10:11], s[48:49]
	v_mov_b64_e32 v[12:13], s[50:51]
	v_mov_b64_e32 v[14:15], s[52:53]
	s_nop 7
	v_max3_f32 v62, v62, v34, v35
	v_max3_f32 v62, v62, v36, v37
	v_max3_f32 v62, v62, v38, v39
	v_max3_f32 v62, v62, v40, v41
	v_max3_f32 v62, v62, v42, v43
	v_max3_f32 v62, v62, v44, v45
	v_max3_f32 v62, v62, v46, v47
	v_max3_f32 v62, v62, v48, v49
	v_mov_b32_e32 v63, v62
	s_nop 1
	v_permlane32_swap_b32_e32 v62, v63
	v_max_f32_e32 v63, v63, v63
	v_max_f32_e32 v62, v62, v62
	v_max_f32_e32 v213, v62, v63
	v_sub_f32_e32 v66, v18, v213
	v_and_b32_e32 v18, 7, v60
	v_sub_f32_e32 v69, v21, v213
	v_sub_f32_e32 v68, v20, v213
	v_sub_f32_e32 v67, v19, v213
	v_bitop3_b32 v19, v196, v60, 7 bitop3:0x78
	v_bitop3_b32 v20, v196, v18, 2 bitop3:0x36
	v_bitop3_b32 v21, v196, v18, 4 bitop3:0x36
	v_bitop3_b32 v18, v196, v18, 6 bitop3:0x36
	v_lshlrev_b32_e32 v19, 4, v19
	v_lshlrev_b32_e32 v20, 4, v20
	v_lshlrev_b32_e32 v21, 4, v21
	v_lshlrev_b32_e32 v18, 4, v18
	v_sub_f32_e32 v81, v33, v213
	v_sub_f32_e32 v80, v32, v213
	v_sub_f32_e32 v79, v31, v213
	v_sub_f32_e32 v78, v30, v213
	v_sub_f32_e32 v77, v29, v213
	v_sub_f32_e32 v76, v28, v213
	v_sub_f32_e32 v75, v27, v213
	v_sub_f32_e32 v74, v26, v213
	v_sub_f32_e32 v73, v25, v213
	v_sub_f32_e32 v72, v24, v213
	v_sub_f32_e32 v71, v23, v213
	v_sub_f32_e32 v70, v22, v213
	v_sub_f32_e32 v97, v49, v213
	v_sub_f32_e32 v96, v48, v213
	v_sub_f32_e32 v95, v47, v213
	v_sub_f32_e32 v94, v46, v213
	v_sub_f32_e32 v93, v45, v213
	v_sub_f32_e32 v92, v44, v213
	v_sub_f32_e32 v91, v43, v213
	v_sub_f32_e32 v90, v42, v213
	v_sub_f32_e32 v89, v41, v213
	v_sub_f32_e32 v88, v40, v213
	v_sub_f32_e32 v87, v39, v213
	v_sub_f32_e32 v86, v38, v213
	v_sub_f32_e32 v85, v37, v213
	v_sub_f32_e32 v84, v36, v213
	v_sub_f32_e32 v83, v35, v213
	v_sub_f32_e32 v82, v34, v213
	v_lshlrev_b32_e32 v250, 4, v60
	v_and_b32_e32 v250, 0x80, v250
	v_add3_u32 v212, v100, v19, v250
	v_add3_u32 v211, v100, v20, v250
	v_add3_u32 v210, v100, v21, v250
	v_add3_u32 v209, v100, v18, v250
	v_xor_b32_e32 v250, 0x80, v212
	v_xor_b32_e32 v251, 0x80, v211
	v_xor_b32_e32 v252, 0x80, v210
	v_xor_b32_e32 v253, 0x80, v209
	v_mov_b64_e32 v[64:65], v[16:17]
	v_mov_b64_e32 v[48:49], v[16:17]
	v_mov_b64_e32 v[32:33], v[16:17]
	v_mov_b64_e32 v[62:63], v[14:15]
	v_mov_b64_e32 v[60:61], v[12:13]
	v_mov_b64_e32 v[58:59], v[10:11]
	v_mov_b64_e32 v[56:57], v[8:9]
	v_mov_b64_e32 v[54:55], v[6:7]
	v_mov_b64_e32 v[52:53], v[4:5]
	v_mov_b64_e32 v[50:51], v[2:3]
	v_mov_b64_e32 v[46:47], v[14:15]
	v_mov_b64_e32 v[44:45], v[12:13]
	v_mov_b64_e32 v[42:43], v[10:11]
	v_mov_b64_e32 v[40:41], v[8:9]
	v_mov_b64_e32 v[38:39], v[6:7]
	v_mov_b64_e32 v[36:37], v[4:5]
	v_mov_b64_e32 v[34:35], v[2:3]
	v_mov_b64_e32 v[30:31], v[14:15]
	v_mov_b64_e32 v[28:29], v[12:13]
	v_mov_b64_e32 v[26:27], v[10:11]
	v_mov_b64_e32 v[24:25], v[8:9]
	v_mov_b64_e32 v[22:23], v[6:7]
	v_mov_b64_e32 v[20:21], v[4:5]
	v_mov_b64_e32 v[18:19], v[2:3]
.LBB0_1308:
	v_lshl_add_u64 v[184:185], s[0:1], 0, v[176:177]
	s_mov_b32 m0, s92
	v_lshl_add_u64 v[98:99], v[184:185], 0, s[28:29]
	v_lshl_add_u64 v[188:189], s[0:1], 0, v[178:179]
	global_load_lds_dwordx4 v[98:99], off
	v_lshl_add_u64 v[98:99], v[188:189], 0, s[28:29]
	s_mov_b32 m0, s93
	v_lshl_add_u64 v[192:193], s[0:1], 0, v[174:175]
	global_load_lds_dwordx4 v[98:99], off
	v_lshl_add_u64 v[98:99], v[192:193], 0, s[30:31]
	s_add_i32 m0, s83, 0x10000
	v_lshl_add_u64 v[186:187], s[0:1], 0, v[180:181]
	s_add_i32 s43, s83, 0x4000
	global_load_lds_dwordx4 v[98:99], off
	v_lshl_add_u64 v[98:99], v[186:187], 0, s[34:35]
	s_mov_b32 m0, s43
	v_lshl_add_u64 v[190:191], s[0:1], 0, v[182:183]
	s_add_i32 s42, s83, 0x6000
	global_load_lds_dwordx4 v[98:99], off
	v_lshl_add_u64 v[98:99], v[190:191], 0, s[34:35]
	s_mov_b32 m0, s42
	s_nop 0
	global_load_lds_dwordx4 v[98:99], off
	ds_read_b128 v[216:219], v212 offset:49152
	s_sub_i32 s2, s33, 64
	s_cmp_le_i32 s2, s82
	s_cselect_b64 s[2:3], -1, 0
	v_cndmask_b32_e64 v98, v229, -v213, s[2:3]
	v_mov_b32_e32 v99, v98
	v_mov_b32_e32 v100, v98
	v_mov_b32_e32 v101, v98
	v_mov_b32_e32 v102, v98
	v_mov_b32_e32 v103, v98
	v_mov_b32_e32 v104, v98
	v_mov_b32_e32 v105, v98
	v_mov_b32_e32 v106, v98
	v_mov_b32_e32 v107, v98
	v_mov_b32_e32 v108, v98
	v_mov_b32_e32 v109, v98
	v_mov_b32_e32 v110, v98
	v_mov_b32_e32 v111, v98
	v_mov_b32_e32 v112, v98
	v_mov_b32_e32 v113, v98
	ds_read_b128 v[220:223], v212 offset:57344
	ds_read_b128 v[230:233], v211 offset:49152
	s_waitcnt lgkmcnt(0)
	v_mfma_f32_32x32x16_bf16 v[114:129], v[216:219], v[158:161], v[98:113]
	v_exp_f32_e32 v168, v66
	v_exp_f32_e32 v169, v82
	v_mfma_f32_32x32x16_bf16 v[98:113], v[220:223], v[158:161], v[98:113]
	ds_read_b128 v[216:219], v211 offset:57344
	v_exp_f32_e32 v170, v67
	v_exp_f32_e32 v171, v83
	v_mfma_f32_32x32x16_bf16 v[114:129], v[230:233], v[154:157], v[114:129]
	ds_read_b128 v[220:223], v210 offset:49152
	v_exp_f32_e32 v172, v68
	v_exp_f32_e32 v173, v84
	s_waitcnt lgkmcnt(0)
	v_mfma_f32_32x32x16_bf16 v[98:113], v[216:219], v[154:157], v[98:113]
	ds_read_b128 v[230:233], v210 offset:57344
	v_exp_f32_e32 v224, v69
	v_exp_f32_e32 v225, v85
	v_mfma_f32_32x32x16_bf16 v[114:129], v[220:223], v[150:153], v[114:129]
	ds_read_b128 v[66:69], v209 offset:49152
	v_exp_f32_e32 v220, v70
	v_exp_f32_e32 v221, v86
	s_waitcnt lgkmcnt(0)
	v_mfma_f32_32x32x16_bf16 v[98:113], v[230:233], v[150:153], v[98:113]
	ds_read_b128 v[82:85], v209 offset:57344
	v_exp_f32_e32 v222, v71
	v_exp_f32_e32 v223, v87
	v_mfma_f32_32x32x16_bf16 v[114:129], v[66:69], v[146:149], v[114:129]
	ds_read_b128 v[216:219], v250 offset:49152
	v_exp_f32_e32 v230, v72
	v_exp_f32_e32 v231, v88
	s_waitcnt lgkmcnt(0)
	v_mfma_f32_32x32x16_bf16 v[98:113], v[82:85], v[146:149], v[98:113]
	ds_read_b128 v[66:69], v250 offset:57344
	v_exp_f32_e32 v232, v73
	v_exp_f32_e32 v233, v89
	v_mfma_f32_32x32x16_bf16 v[114:129], v[216:219], v[142:145], v[114:129]
	ds_read_b128 v[70:73], v251 offset:49152
	v_exp_f32_e32 v234, v74
	v_exp_f32_e32 v235, v90
	s_waitcnt lgkmcnt(0)
	v_mfma_f32_32x32x16_bf16 v[98:113], v[66:69], v[142:145], v[98:113]
	ds_read_b128 v[82:85], v251 offset:57344
	v_exp_f32_e32 v236, v75
	v_exp_f32_e32 v237, v91
	v_mfma_f32_32x32x16_bf16 v[114:129], v[70:73], v[138:141], v[114:129]
	ds_read_b128 v[66:69], v252 offset:49152
	v_exp_f32_e32 v238, v76
	v_exp_f32_e32 v239, v92
	s_waitcnt lgkmcnt(0)
	v_mfma_f32_32x32x16_bf16 v[98:113], v[82:85], v[138:141], v[98:113]
	ds_read_b128 v[70:73], v252 offset:57344
	v_exp_f32_e32 v240, v77
	v_exp_f32_e32 v241, v93
	v_mfma_f32_32x32x16_bf16 v[114:129], v[66:69], v[134:137], v[114:129]
	ds_read_b128 v[74:77], v253 offset:49152
	v_exp_f32_e32 v242, v78
	v_exp_f32_e32 v243, v94
	s_waitcnt lgkmcnt(0)
	v_mfma_f32_32x32x16_bf16 v[98:113], v[70:73], v[134:137], v[98:113]
	ds_read_b128 v[66:69], v253 offset:57344
	v_exp_f32_e32 v244, v79
	v_exp_f32_e32 v245, v95
	v_mfma_f32_32x32x16_bf16 v[114:129], v[74:77], v[130:133], v[114:129]
	v_add_u32_e32 v219, v214, v201
	ds_read_b128 v[70:73], v219
	ds_read_b128 v[82:85], v200
	v_exp_f32_e32 v246, v80
	v_exp_f32_e32 v247, v96
	s_waitcnt lgkmcnt(0)
	v_mfma_f32_32x32x16_bf16 v[98:113], v[66:69], v[130:133], v[98:113]
	ds_read_b128 v[74:77], v219 offset:4096
	v_exp_f32_e32 v248, v81
	v_exp_f32_e32 v249, v97
	v_mfma_f32_32x32x16_bf16 v[114:129], v[70:73], v[82:85], v[114:129]
	v_add_u32_e32 v216, v214, v202
	ds_read_b128 v[78:81], v216
	ds_read_b128 v[86:89], v200 offset:1024
	v_cvt_pk_bf16_f32 v66, v168, v170
	v_cvt_pk_bf16_f32 v67, v172, v224
	v_cvt_pk_bf16_f32 v68, v220, v222
	v_cvt_pk_bf16_f32 v69, v230, v232
	s_nop 0
	v_permlane32_swap_b32_e32 v66, v68
	v_permlane32_swap_b32_e32 v67, v69
	s_waitcnt lgkmcnt(0)
	v_mfma_f32_32x32x16_bf16 v[98:113], v[74:77], v[82:85], v[98:113]
	ds_read_b128 v[90:93], v216 offset:4096
	v_mfma_f32_32x32x16_bf16 v[114:129], v[78:81], v[86:89], v[114:129]
	v_add_u32_e32 v217, v214, v203
	ds_read_b128 v[74:77], v217
	ds_read_b128 v[82:85], v200 offset:2048
	v_cvt_pk_bf16_f32 v70, v234, v236
	v_cvt_pk_bf16_f32 v71, v238, v240
	v_cvt_pk_bf16_f32 v72, v242, v244
	v_cvt_pk_bf16_f32 v73, v246, v248
	s_nop 0
	v_permlane32_swap_b32_e32 v70, v72
	v_permlane32_swap_b32_e32 v71, v73
	s_waitcnt lgkmcnt(0)
	v_mfma_f32_32x32x16_bf16 v[98:113], v[90:93], v[86:89], v[98:113]
	ds_read_b128 v[78:81], v217 offset:4096
	v_mfma_f32_32x32x16_bf16 v[114:129], v[74:77], v[82:85], v[114:129]
	v_add_u32_e32 v218, v214, v204
	ds_read_b128 v[86:89], v218
	ds_read_b128 v[90:93], v200 offset:3072
	v_cvt_pk_bf16_f32 v74, v169, v171
	v_cvt_pk_bf16_f32 v75, v173, v225
	v_cvt_pk_bf16_f32 v76, v221, v223
	v_cvt_pk_bf16_f32 v77, v231, v233
	s_nop 0
	v_permlane32_swap_b32_e32 v74, v76
	v_permlane32_swap_b32_e32 v75, v77
	s_waitcnt lgkmcnt(0)
	v_mfma_f32_32x32x16_bf16 v[98:113], v[78:81], v[82:85], v[98:113]
	ds_read_b128 v[94:97], v218 offset:4096
	v_mfma_f32_32x32x16_bf16 v[114:129], v[86:89], v[90:93], v[114:129]
	v_cvt_pk_bf16_f32 v80, v235, v237
	v_cvt_pk_bf16_f32 v81, v239, v241
	v_cvt_pk_bf16_f32 v82, v243, v245
	v_cvt_pk_bf16_f32 v83, v247, v249
	s_nop 0
	v_permlane32_swap_b32_e32 v80, v82
	v_permlane32_swap_b32_e32 v81, v83
	v_add_f32_e32 v78, 0, v168
	v_add_f32_e32 v78, v78, v169
	v_add_f32_e32 v78, v170, v78
	v_add_f32_e32 v78, v171, v78
	v_add_f32_e32 v78, v172, v78
	v_add_f32_e32 v78, v173, v78
	v_add_f32_e32 v78, v224, v78
	v_add_f32_e32 v78, v225, v78
	v_add_f32_e32 v78, v220, v78
	v_add_f32_e32 v78, v221, v78
	v_add_f32_e32 v78, v222, v78
	v_add_f32_e32 v78, v223, v78
	v_add_f32_e32 v78, v230, v78
	v_add_f32_e32 v78, v231, v78
	v_add_f32_e32 v78, v232, v78
	v_add_f32_e32 v78, v233, v78
	v_add_f32_e32 v78, v234, v78
	v_add_f32_e32 v78, v235, v78
	v_add_f32_e32 v78, v236, v78
	v_add_f32_e32 v78, v237, v78
	v_add_f32_e32 v78, v238, v78
	v_add_f32_e32 v78, v239, v78
	v_add_f32_e32 v78, v240, v78
	v_add_f32_e32 v78, v241, v78
	s_waitcnt lgkmcnt(0)
	v_mfma_f32_32x32x16_bf16 v[98:113], v[94:97], v[90:93], v[98:113]
	v_add_f32_e32 v78, v242, v78
	v_add_f32_e32 v78, v243, v78
	v_add_f32_e32 v78, v244, v78
	v_add_f32_e32 v78, v245, v78
	v_add_f32_e32 v78, v246, v78
	v_add_f32_e32 v78, v247, v78
	v_add_f32_e32 v78, v248, v78
	v_add_f32_e32 v220, v249, v78
	v_mov_b32_e32 v221, v220
	s_nop 1
	v_permlane32_swap_b32_e32 v220, v221
	ds_read_b64_tr_b16 v[84:85], v199 offset:0
	ds_read_b64_tr_b16 v[86:87], v199 offset:0x800
	ds_read_b64_tr_b16 v[88:89], v199 offset:0x1000
	ds_read_b64_tr_b16 v[90:91], v199 offset:0x1800
	ds_read_b64_tr_b16 v[92:93], v199 offset:0x2000
	ds_read_b64_tr_b16 v[94:95], v199 offset:0x2800
	ds_read_b64_tr_b16 v[222:223], v199 offset:0x3000
	ds_read_b64_tr_b16 v[224:225], v199 offset:0x3800
	s_waitcnt lgkmcnt(0)
	s_nop 0
	v_mfma_f32_32x32x16_bf16 v[2:17], v[66:69], v[84:87], v[2:17]
	v_max_f32_e32 v78, v115, v115
	v_max_f32_e32 v79, v114, v114
	v_max_f32_e32 v78, v79, v78
	v_max3_f32 v78, v78, v116, v117
	v_max3_f32 v78, v78, v118, v119
	v_max3_f32 v78, v78, v120, v121
	v_max3_f32 v78, v78, v122, v123
	v_mfma_f32_32x32x16_bf16 v[2:17], v[70:73], v[88:91], v[2:17]
	v_max3_f32 v78, v78, v124, v125
	v_max3_f32 v78, v78, v126, v127
	v_max3_f32 v78, v78, v128, v129
	v_max3_f32 v78, v78, v98, v99
	v_max3_f32 v78, v78, v100, v101
	v_max3_f32 v78, v78, v102, v103
	v_max3_f32 v78, v78, v104, v105
	v_mfma_f32_32x32x16_bf16 v[2:17], v[74:77], v[92:95], v[2:17]
	v_max3_f32 v78, v78, v106, v107
	v_max3_f32 v78, v78, v108, v109
	v_max3_f32 v78, v78, v110, v111
	v_max3_f32 v78, v78, v112, v113
	v_mfma_f32_32x32x16_bf16 v[2:17], v[80:83], v[222:225], v[2:17]
	ds_read_b64_tr_b16 v[84:85], v199 offset:0x200
	ds_read_b64_tr_b16 v[86:87], v199 offset:0xa00
	ds_read_b64_tr_b16 v[88:89], v199 offset:0x1200
	ds_read_b64_tr_b16 v[90:91], v199 offset:0x1a00
	ds_read_b64_tr_b16 v[92:93], v199 offset:0x2200
	ds_read_b64_tr_b16 v[94:95], v199 offset:0x2a00
	ds_read_b64_tr_b16 v[222:223], v199 offset:0x3200
	ds_read_b64_tr_b16 v[224:225], v199 offset:0x3a00
	s_waitcnt lgkmcnt(0)
	s_nop 0
	v_mfma_f32_32x32x16_bf16 v[50:65], v[66:69], v[84:87], v[50:65]
	v_mov_b32_e32 v79, v78
	s_nop 1
	v_permlane32_swap_b32_e32 v78, v79
	v_max_f32_e32 v79, v79, v79
	v_max_f32_e32 v78, v78, v78
	v_max_f32_e32 v78, v78, v79
	v_mfma_f32_32x32x16_bf16 v[50:65], v[70:73], v[88:91], v[50:65]
	v_mfma_f32_32x32x16_bf16 v[50:65], v[74:77], v[92:95], v[50:65]
	v_mfma_f32_32x32x16_bf16 v[50:65], v[80:83], v[222:225], v[50:65]
	ds_read_b64_tr_b16 v[84:85], v199 offset:0x400
	ds_read_b64_tr_b16 v[86:87], v199 offset:0xc00
	ds_read_b64_tr_b16 v[88:89], v199 offset:0x1400
	ds_read_b64_tr_b16 v[90:91], v199 offset:0x1c00
	ds_read_b64_tr_b16 v[92:93], v199 offset:0x2400
	ds_read_b64_tr_b16 v[94:95], v199 offset:0x2c00
	ds_read_b64_tr_b16 v[222:223], v199 offset:0x3400
	ds_read_b64_tr_b16 v[224:225], v199 offset:0x3c00
	s_waitcnt lgkmcnt(0)
	s_nop 0
	v_mfma_f32_32x32x16_bf16 v[34:49], v[66:69], v[84:87], v[34:49]
	v_mfma_f32_32x32x16_bf16 v[34:49], v[70:73], v[88:91], v[34:49]
	v_mfma_f32_32x32x16_bf16 v[34:49], v[74:77], v[92:95], v[34:49]
	v_mfma_f32_32x32x16_bf16 v[34:49], v[80:83], v[222:225], v[34:49]
	ds_read_b64_tr_b16 v[84:85], v199 offset:0x600
	ds_read_b64_tr_b16 v[86:87], v199 offset:0xe00
	ds_read_b64_tr_b16 v[88:89], v199 offset:0x1600
	ds_read_b64_tr_b16 v[90:91], v199 offset:0x1e00
	ds_read_b64_tr_b16 v[92:93], v199 offset:0x2600
	ds_read_b64_tr_b16 v[94:95], v199 offset:0x2e00
	ds_read_b64_tr_b16 v[222:223], v199 offset:0x3600
	ds_read_b64_tr_b16 v[224:225], v199 offset:0x3e00
	s_waitcnt lgkmcnt(0)
	s_nop 0
	v_mfma_f32_32x32x16_bf16 v[18:33], v[66:69], v[84:87], v[18:33]
	v_cmp_ge_f32_e32 vcc, s90, v78
	s_cmp_eq_u64 vcc, exec
	v_mfma_f32_32x32x16_bf16 v[18:33], v[70:73], v[88:91], v[18:33]
	v_mfma_f32_32x32x16_bf16 v[18:33], v[74:77], v[92:95], v[18:33]
	v_mfma_f32_32x32x16_bf16 v[18:33], v[80:83], v[222:225], v[18:33]
	s_cbranch_scc0 .LBB0_1323
	v_mov_b32_e32 v222, 1.0

.LBB0_1316:
	s_mov_b32 m0, s83
	v_lshl_add_u64 v[66:67], v[186:187], 0, s[36:37]
	global_load_lds_dwordx4 v[66:67], off
	v_lshl_add_u64 v[66:67], v[190:191], 0, s[36:37]
	s_mov_b32 m0, s96
	s_nop 0
	global_load_lds_dwordx4 v[66:67], off
	ds_read_b128 v[184:187], v212 offset:32768
	s_cmp_le_i32 s33, s82
	s_cselect_b64 s[2:3], -1, 0
	v_cndmask_b32_e64 v82, v229, -v213, s[2:3]
	v_mov_b32_e32 v83, v82
	v_mov_b32_e32 v84, v82
	v_mov_b32_e32 v85, v82
	v_mov_b32_e32 v86, v82
	v_mov_b32_e32 v87, v82
	v_mov_b32_e32 v88, v82
	v_mov_b32_e32 v89, v82
	v_mov_b32_e32 v90, v82
	v_mov_b32_e32 v91, v82
	v_mov_b32_e32 v92, v82
	v_mov_b32_e32 v93, v82
	v_mov_b32_e32 v94, v82
	v_mov_b32_e32 v95, v82
	v_mov_b32_e32 v96, v82
	v_mov_b32_e32 v97, v82
	ds_read_b128 v[188:191], v212 offset:40960
	ds_read_b128 v[230:233], v211 offset:32768
	s_waitcnt lgkmcnt(0)
	v_mfma_f32_32x32x16_bf16 v[66:81], v[184:187], v[158:161], v[82:97]
	v_exp_f32_e32 v168, v114
	v_exp_f32_e32 v169, v98
	v_mfma_f32_32x32x16_bf16 v[82:97], v[188:191], v[158:161], v[82:97]
	ds_read_b128 v[184:187], v211 offset:40960
	v_exp_f32_e32 v170, v115
	v_exp_f32_e32 v171, v99
	v_mfma_f32_32x32x16_bf16 v[66:81], v[230:233], v[154:157], v[66:81]
	ds_read_b128 v[188:191], v210 offset:32768
	v_exp_f32_e32 v172, v116
	v_exp_f32_e32 v173, v100
	s_waitcnt lgkmcnt(0)
	v_mfma_f32_32x32x16_bf16 v[82:97], v[184:187], v[154:157], v[82:97]
	ds_read_b128 v[230:233], v210 offset:40960
	v_exp_f32_e32 v192, v117
	v_exp_f32_e32 v193, v101
	v_mfma_f32_32x32x16_bf16 v[66:81], v[188:191], v[150:153], v[66:81]
	ds_read_b128 v[98:101], v209 offset:32768
	v_exp_f32_e32 v188, v118
	v_exp_f32_e32 v189, v102
	s_waitcnt lgkmcnt(0)
	v_mfma_f32_32x32x16_bf16 v[82:97], v[230:233], v[150:153], v[82:97]
	ds_read_b128 v[114:117], v209 offset:40960
	v_exp_f32_e32 v190, v119
	v_exp_f32_e32 v191, v103
	v_mfma_f32_32x32x16_bf16 v[66:81], v[98:101], v[146:149], v[66:81]
	ds_read_b128 v[184:187], v250 offset:32768
	v_exp_f32_e32 v223, v120
	v_exp_f32_e32 v224, v104
	s_waitcnt lgkmcnt(0)
	v_mfma_f32_32x32x16_bf16 v[82:97], v[114:117], v[146:149], v[82:97]
	ds_read_b128 v[98:101], v250 offset:40960
	v_exp_f32_e32 v225, v121
	v_exp_f32_e32 v230, v105
	v_mfma_f32_32x32x16_bf16 v[66:81], v[184:187], v[142:145], v[66:81]
	ds_read_b128 v[102:105], v251 offset:32768
	v_exp_f32_e32 v184, v122
	v_exp_f32_e32 v185, v106
	s_waitcnt lgkmcnt(0)
	v_mfma_f32_32x32x16_bf16 v[82:97], v[98:101], v[142:145], v[82:97]
	ds_read_b128 v[114:117], v251 offset:40960
	v_exp_f32_e32 v186, v123
	v_exp_f32_e32 v187, v107
	v_mfma_f32_32x32x16_bf16 v[66:81], v[102:105], v[138:141], v[66:81]
	ds_read_b128 v[98:101], v252 offset:32768
	v_exp_f32_e32 v231, v124
	v_exp_f32_e32 v232, v108
	s_waitcnt lgkmcnt(0)
	v_mfma_f32_32x32x16_bf16 v[82:97], v[114:117], v[138:141], v[82:97]
	ds_read_b128 v[102:105], v252 offset:40960
	v_exp_f32_e32 v233, v125
	v_exp_f32_e32 v234, v109
	v_mfma_f32_32x32x16_bf16 v[66:81], v[98:101], v[134:137], v[66:81]
	ds_read_b128 v[106:109], v253 offset:32768
	v_exp_f32_e32 v235, v126
	v_exp_f32_e32 v236, v110
	s_waitcnt lgkmcnt(0)
	v_mfma_f32_32x32x16_bf16 v[82:97], v[102:105], v[134:137], v[82:97]
	ds_read_b128 v[98:101], v253 offset:40960
	v_exp_f32_e32 v237, v127
	v_exp_f32_e32 v238, v111
	v_mfma_f32_32x32x16_bf16 v[66:81], v[106:109], v[130:133], v[66:81]
	ds_read_b128 v[102:105], v205
	ds_read_b128 v[114:117], v200
	v_exp_f32_e32 v239, v128
	v_exp_f32_e32 v240, v112
	s_waitcnt lgkmcnt(0)
	v_mfma_f32_32x32x16_bf16 v[82:97], v[98:101], v[130:133], v[82:97]
	ds_read_b128 v[106:109], v205 offset:4096
	v_exp_f32_e32 v241, v129
	v_exp_f32_e32 v242, v113
	v_mfma_f32_32x32x16_bf16 v[66:81], v[102:105], v[114:117], v[66:81]
	ds_read_b128 v[110:113], v206
	ds_read_b128 v[118:121], v200 offset:1024
	v_cvt_pk_bf16_f32 v98, v168, v170
	v_cvt_pk_bf16_f32 v99, v172, v192
	v_cvt_pk_bf16_f32 v100, v188, v190
	v_cvt_pk_bf16_f32 v101, v223, v225
	s_nop 0
	v_permlane32_swap_b32_e32 v98, v100
	v_permlane32_swap_b32_e32 v99, v101
	s_waitcnt lgkmcnt(0)
	v_mfma_f32_32x32x16_bf16 v[82:97], v[106:109], v[114:117], v[82:97]
	ds_read_b128 v[122:125], v206 offset:4096
	v_mfma_f32_32x32x16_bf16 v[66:81], v[110:113], v[118:121], v[66:81]
	ds_read_b128 v[106:109], v207
	ds_read_b128 v[114:117], v200 offset:2048
	v_cvt_pk_bf16_f32 v102, v184, v186
	v_cvt_pk_bf16_f32 v103, v231, v233
	v_cvt_pk_bf16_f32 v104, v235, v237
	v_cvt_pk_bf16_f32 v105, v239, v241
	s_nop 0
	v_permlane32_swap_b32_e32 v102, v104
	v_permlane32_swap_b32_e32 v103, v105
	s_waitcnt lgkmcnt(0)
	v_mfma_f32_32x32x16_bf16 v[82:97], v[122:125], v[118:121], v[82:97]
	ds_read_b128 v[110:113], v207 offset:4096
	v_mfma_f32_32x32x16_bf16 v[66:81], v[106:109], v[114:117], v[66:81]
	ds_read_b128 v[118:121], v208
	ds_read_b128 v[122:125], v200 offset:3072
	v_cvt_pk_bf16_f32 v106, v169, v171
	v_cvt_pk_bf16_f32 v107, v173, v193
	v_cvt_pk_bf16_f32 v108, v189, v191
	v_cvt_pk_bf16_f32 v109, v224, v230
	s_nop 0
	v_permlane32_swap_b32_e32 v106, v108
	v_permlane32_swap_b32_e32 v107, v109
	s_waitcnt lgkmcnt(0)
	v_mfma_f32_32x32x16_bf16 v[82:97], v[110:113], v[114:117], v[82:97]
	ds_read_b128 v[126:129], v208 offset:4096
	v_mfma_f32_32x32x16_bf16 v[66:81], v[118:121], v[122:125], v[66:81]
	v_cvt_pk_bf16_f32 v114, v185, v187
	v_cvt_pk_bf16_f32 v115, v232, v234
	v_cvt_pk_bf16_f32 v116, v236, v238
	v_cvt_pk_bf16_f32 v117, v240, v242
	s_nop 0
	v_permlane32_swap_b32_e32 v114, v116
	v_permlane32_swap_b32_e32 v115, v117
	v_add_f32_e32 v110, 0, v168
	v_add_f32_e32 v110, v169, v110
	v_add_f32_e32 v110, v170, v110
	v_add_f32_e32 v110, v171, v110
	v_add_f32_e32 v110, v172, v110
	v_add_f32_e32 v110, v173, v110
	v_add_f32_e32 v110, v192, v110
	v_add_f32_e32 v110, v193, v110
	v_add_f32_e32 v110, v188, v110
	v_add_f32_e32 v110, v189, v110
	v_add_f32_e32 v110, v190, v110
	v_add_f32_e32 v110, v191, v110
	v_add_f32_e32 v110, v223, v110
	v_add_f32_e32 v110, v224, v110
	v_add_f32_e32 v110, v225, v110
	v_add_f32_e32 v110, v230, v110
	v_add_f32_e32 v110, v184, v110
	v_add_f32_e32 v110, v185, v110
	v_add_f32_e32 v110, v186, v110
	v_add_f32_e32 v110, v187, v110
	v_add_f32_e32 v110, v231, v110
	v_add_f32_e32 v110, v232, v110
	v_add_f32_e32 v110, v233, v110
	v_add_f32_e32 v110, v234, v110
	s_waitcnt lgkmcnt(0)
	v_mfma_f32_32x32x16_bf16 v[82:97], v[126:129], v[122:125], v[82:97]
	v_add_f32_e32 v110, v235, v110
	v_add_f32_e32 v110, v236, v110
	v_add_f32_e32 v110, v237, v110
	v_add_f32_e32 v110, v238, v110
	v_add_f32_e32 v110, v239, v110
	v_add_f32_e32 v110, v240, v110
	v_add_f32_e32 v110, v241, v110
	v_add_f32_e32 v110, v242, v110
	v_mov_b32_e32 v111, v110
	s_nop 1
	v_permlane32_swap_b32_e32 v110, v111
	ds_read_b64_tr_b16 v[118:119], v199 offset:0x4000
	ds_read_b64_tr_b16 v[120:121], v199 offset:0x4800
	ds_read_b64_tr_b16 v[122:123], v199 offset:0x5000
	ds_read_b64_tr_b16 v[124:125], v199 offset:0x5800
	ds_read_b64_tr_b16 v[126:127], v199 offset:0x6000
	ds_read_b64_tr_b16 v[128:129], v199 offset:0x6800
	ds_read_b64_tr_b16 v[184:185], v199 offset:0x7000
	ds_read_b64_tr_b16 v[186:187], v199 offset:0x7800
	s_waitcnt lgkmcnt(0)
	s_nop 0
	v_mfma_f32_32x32x16_bf16 v[2:17], v[98:101], v[118:121], v[2:17]
	v_max_f32_e32 v112, v67, v67
	v_max_f32_e32 v113, v66, v66
	v_max_f32_e32 v112, v113, v112
	v_max3_f32 v112, v112, v68, v69
	v_max3_f32 v112, v112, v70, v71
	v_max3_f32 v112, v112, v72, v73
	v_max3_f32 v112, v112, v74, v75
	v_mfma_f32_32x32x16_bf16 v[2:17], v[102:105], v[122:125], v[2:17]
	v_max3_f32 v112, v112, v76, v77
	v_max3_f32 v112, v112, v78, v79
	v_max3_f32 v112, v112, v80, v81
	v_max3_f32 v112, v112, v82, v83
	v_max3_f32 v112, v112, v84, v85
	v_max3_f32 v112, v112, v86, v87
	v_max3_f32 v112, v112, v88, v89
	v_mfma_f32_32x32x16_bf16 v[2:17], v[106:109], v[126:129], v[2:17]
	v_max3_f32 v112, v112, v90, v91
	v_max3_f32 v112, v112, v92, v93
	v_max3_f32 v112, v112, v94, v95
	v_max3_f32 v112, v112, v96, v97
	v_mfma_f32_32x32x16_bf16 v[2:17], v[114:117], v[184:187], v[2:17]
	ds_read_b64_tr_b16 v[118:119], v199 offset:0x4200
	ds_read_b64_tr_b16 v[120:121], v199 offset:0x4a00
	ds_read_b64_tr_b16 v[122:123], v199 offset:0x5200
	ds_read_b64_tr_b16 v[124:125], v199 offset:0x5a00
	ds_read_b64_tr_b16 v[126:127], v199 offset:0x6200
	ds_read_b64_tr_b16 v[128:129], v199 offset:0x6a00
	ds_read_b64_tr_b16 v[184:185], v199 offset:0x7200
	ds_read_b64_tr_b16 v[186:187], v199 offset:0x7a00
	s_waitcnt lgkmcnt(0)
	s_nop 0
	v_mfma_f32_32x32x16_bf16 v[50:65], v[98:101], v[118:121], v[50:65]
	v_mov_b32_e32 v113, v112
	s_nop 1
	v_permlane32_swap_b32_e32 v112, v113
	v_max_f32_e32 v113, v113, v113
	v_max_f32_e32 v112, v112, v112
	v_max_f32_e32 v112, v112, v113
	v_mfma_f32_32x32x16_bf16 v[50:65], v[102:105], v[122:125], v[50:65]
	v_mfma_f32_32x32x16_bf16 v[50:65], v[106:109], v[126:129], v[50:65]
	v_mfma_f32_32x32x16_bf16 v[50:65], v[114:117], v[184:187], v[50:65]
	ds_read_b64_tr_b16 v[118:119], v199 offset:0x4400
	ds_read_b64_tr_b16 v[120:121], v199 offset:0x4c00
	ds_read_b64_tr_b16 v[122:123], v199 offset:0x5400
	ds_read_b64_tr_b16 v[124:125], v199 offset:0x5c00
	ds_read_b64_tr_b16 v[126:127], v199 offset:0x6400
	ds_read_b64_tr_b16 v[128:129], v199 offset:0x6c00
	ds_read_b64_tr_b16 v[184:185], v199 offset:0x7400
	ds_read_b64_tr_b16 v[186:187], v199 offset:0x7c00
	s_waitcnt lgkmcnt(0)
	s_nop 0
	v_mfma_f32_32x32x16_bf16 v[34:49], v[98:101], v[118:121], v[34:49]
	v_mfma_f32_32x32x16_bf16 v[34:49], v[102:105], v[122:125], v[34:49]
	v_mfma_f32_32x32x16_bf16 v[34:49], v[106:109], v[126:129], v[34:49]
	v_mfma_f32_32x32x16_bf16 v[34:49], v[114:117], v[184:187], v[34:49]
	ds_read_b64_tr_b16 v[118:119], v199 offset:0x4600
	ds_read_b64_tr_b16 v[120:121], v199 offset:0x4e00
	ds_read_b64_tr_b16 v[122:123], v199 offset:0x5600
	ds_read_b64_tr_b16 v[124:125], v199 offset:0x5e00
	ds_read_b64_tr_b16 v[126:127], v199 offset:0x6600
	ds_read_b64_tr_b16 v[128:129], v199 offset:0x6e00
	ds_read_b64_tr_b16 v[186:187], v199 offset:0x7600
	ds_read_b64_tr_b16 v[188:189], v199 offset:0x7e00
	s_waitcnt lgkmcnt(0)
	s_nop 0
	v_mfma_f32_32x32x16_bf16 v[18:33], v[98:101], v[118:121], v[18:33]
	v_cmp_ge_f32_e32 vcc, s90, v112
	v_mov_b32_e32 v184, 1.0
	s_cmp_eq_u64 vcc, exec
	v_mfma_f32_32x32x16_bf16 v[18:33], v[102:105], v[122:125], v[18:33]
	v_mfma_f32_32x32x16_bf16 v[18:33], v[106:109], v[126:129], v[18:33]
	v_mfma_f32_32x32x16_bf16 v[18:33], v[114:117], v[186:189], v[18:33]
	s_cbranch_scc0 .LBB0_1324

.LBB0_1325:
	s_or_b32 s33, s80, 3
	s_lshl_b32 s2, s33, 18
	s_add_u32 s2, s22, s2
	s_addc_u32 s3, s23, 0
	s_mov_b32 m0, s43
	v_lshl_add_u64 v[98:99], v[166:167], 1, s[2:3]
	global_load_lds_dwordx4 v[98:99], off
	v_lshl_add_u64 v[98:99], v[164:165], 1, s[2:3]
	s_mov_b32 m0, s42
	s_nop 0
	global_load_lds_dwordx4 v[98:99], off
	ds_read_b128 v[174:177], v212 offset:49152
	s_lshl_b32 s2, s33, 6
	s_cmp_le_i32 s2, s82
	s_cselect_b64 s[2:3], -1, 0
	v_cndmask_b32_e64 v98, v229, -v213, s[2:3]
	v_mov_b32_e32 v99, v98
	v_mov_b32_e32 v100, v98
	v_mov_b32_e32 v101, v98
	v_mov_b32_e32 v102, v98
	v_mov_b32_e32 v103, v98
	v_mov_b32_e32 v104, v98
	v_mov_b32_e32 v105, v98
	v_mov_b32_e32 v106, v98
	v_mov_b32_e32 v107, v98
	v_mov_b32_e32 v108, v98
	v_mov_b32_e32 v109, v98
	v_mov_b32_e32 v110, v98
	v_mov_b32_e32 v111, v98
	v_mov_b32_e32 v112, v98
	v_mov_b32_e32 v113, v98
	ds_read_b128 v[178:181], v212 offset:57344
	ds_read_b128 v[186:189], v211 offset:49152
	s_waitcnt lgkmcnt(0)
	v_mfma_f32_32x32x16_bf16 v[114:129], v[174:177], v[158:161], v[98:113]
	v_exp_f32_e32 v164, v66
	v_exp_f32_e32 v165, v82
	v_mfma_f32_32x32x16_bf16 v[98:113], v[178:181], v[158:161], v[98:113]
	ds_read_b128 v[174:177], v211 offset:57344
	v_exp_f32_e32 v166, v67
	v_exp_f32_e32 v168, v83
	v_mfma_f32_32x32x16_bf16 v[114:129], v[186:189], v[154:157], v[114:129]
	ds_read_b128 v[158:161], v210 offset:49152
	v_exp_f32_e32 v169, v68
	v_exp_f32_e32 v170, v84
	s_waitcnt lgkmcnt(0)
	v_mfma_f32_32x32x16_bf16 v[98:113], v[174:177], v[154:157], v[98:113]
	ds_read_b128 v[178:181], v210 offset:57344
	v_exp_f32_e32 v154, v69
	v_exp_f32_e32 v155, v85
	v_mfma_f32_32x32x16_bf16 v[114:129], v[158:161], v[150:153], v[114:129]
	ds_read_b128 v[66:69], v209 offset:49152
	v_exp_f32_e32 v156, v70
	v_exp_f32_e32 v157, v86
	s_waitcnt lgkmcnt(0)
	v_mfma_f32_32x32x16_bf16 v[98:113], v[178:181], v[150:153], v[98:113]
	ds_read_b128 v[82:85], v209 offset:57344
	v_exp_f32_e32 v158, v71
	v_exp_f32_e32 v159, v87
	v_mfma_f32_32x32x16_bf16 v[114:129], v[66:69], v[146:149], v[114:129]
	ds_read_b128 v[150:153], v250 offset:49152
	v_exp_f32_e32 v160, v72
	v_exp_f32_e32 v161, v88
	s_waitcnt lgkmcnt(0)
	v_mfma_f32_32x32x16_bf16 v[98:113], v[82:85], v[146:149], v[98:113]
	ds_read_b128 v[66:69], v250 offset:57344
	v_exp_f32_e32 v171, v73
	v_exp_f32_e32 v172, v89
	v_mfma_f32_32x32x16_bf16 v[114:129], v[150:153], v[142:145], v[114:129]
	ds_read_b128 v[70:73], v251 offset:49152
	v_exp_f32_e32 v146, v74
	v_exp_f32_e32 v147, v90
	s_waitcnt lgkmcnt(0)
	v_mfma_f32_32x32x16_bf16 v[98:113], v[66:69], v[142:145], v[98:113]
	ds_read_b128 v[82:85], v251 offset:57344
	v_exp_f32_e32 v148, v75
	v_exp_f32_e32 v149, v91
	v_mfma_f32_32x32x16_bf16 v[114:129], v[70:73], v[138:141], v[114:129]
	ds_read_b128 v[66:69], v252 offset:49152
	v_exp_f32_e32 v142, v76
	v_exp_f32_e32 v143, v92
	s_waitcnt lgkmcnt(0)
	v_mfma_f32_32x32x16_bf16 v[98:113], v[82:85], v[138:141], v[98:113]
	ds_read_b128 v[70:73], v252 offset:57344
	v_exp_f32_e32 v144, v77
	v_exp_f32_e32 v145, v93
	v_mfma_f32_32x32x16_bf16 v[114:129], v[66:69], v[134:137], v[114:129]
	ds_read_b128 v[74:77], v253 offset:49152
	v_exp_f32_e32 v138, v78
	v_exp_f32_e32 v139, v94
	s_waitcnt lgkmcnt(0)
	v_mfma_f32_32x32x16_bf16 v[98:113], v[70:73], v[134:137], v[98:113]
	ds_read_b128 v[66:69], v253 offset:57344
	v_exp_f32_e32 v140, v79
	v_exp_f32_e32 v141, v95
	v_mfma_f32_32x32x16_bf16 v[114:129], v[74:77], v[130:133], v[114:129]
	ds_read_b128 v[70:73], v219
	ds_read_b128 v[82:85], v200
	v_exp_f32_e32 v134, v80
	v_exp_f32_e32 v135, v96
	s_waitcnt lgkmcnt(0)
	v_mfma_f32_32x32x16_bf16 v[98:113], v[66:69], v[130:133], v[98:113]
	ds_read_b128 v[74:77], v219 offset:4096
	v_exp_f32_e32 v136, v81
	v_exp_f32_e32 v137, v97
	v_mfma_f32_32x32x16_bf16 v[114:129], v[70:73], v[82:85], v[114:129]
	ds_read_b128 v[78:81], v216
	ds_read_b128 v[86:89], v200 offset:1024
	v_cvt_pk_bf16_f32 v66, v164, v166
	v_cvt_pk_bf16_f32 v67, v169, v154
	v_cvt_pk_bf16_f32 v68, v156, v158
	v_cvt_pk_bf16_f32 v69, v160, v171
	s_nop 0
	v_permlane32_swap_b32_e32 v66, v68
	v_permlane32_swap_b32_e32 v67, v69
	s_waitcnt lgkmcnt(0)
	v_mfma_f32_32x32x16_bf16 v[98:113], v[74:77], v[82:85], v[98:113]
	ds_read_b128 v[90:93], v216 offset:4096
	v_mfma_f32_32x32x16_bf16 v[114:129], v[78:81], v[86:89], v[114:129]
	ds_read_b128 v[74:77], v217
	ds_read_b128 v[82:85], v200 offset:2048
	v_cvt_pk_bf16_f32 v70, v146, v148
	v_cvt_pk_bf16_f32 v71, v142, v144
	v_cvt_pk_bf16_f32 v72, v138, v140
	v_cvt_pk_bf16_f32 v73, v134, v136
	s_nop 0
	v_permlane32_swap_b32_e32 v70, v72
	v_permlane32_swap_b32_e32 v71, v73
	s_waitcnt lgkmcnt(0)
	v_mfma_f32_32x32x16_bf16 v[98:113], v[90:93], v[86:89], v[98:113]
	ds_read_b128 v[78:81], v217 offset:4096
	v_mfma_f32_32x32x16_bf16 v[114:129], v[74:77], v[82:85], v[114:129]
	ds_read_b128 v[86:89], v218
	ds_read_b128 v[90:93], v200 offset:3072
	v_cvt_pk_bf16_f32 v74, v165, v168
	v_cvt_pk_bf16_f32 v75, v170, v155
	v_cvt_pk_bf16_f32 v76, v157, v159
	v_cvt_pk_bf16_f32 v77, v161, v172
	s_nop 0
	v_permlane32_swap_b32_e32 v74, v76
	v_permlane32_swap_b32_e32 v75, v77
	s_waitcnt lgkmcnt(0)
	v_mfma_f32_32x32x16_bf16 v[98:113], v[78:81], v[82:85], v[98:113]
	ds_read_b128 v[94:97], v218 offset:4096
	v_mfma_f32_32x32x16_bf16 v[114:129], v[86:89], v[90:93], v[114:129]
	v_cvt_pk_bf16_f32 v82, v147, v149
	v_cvt_pk_bf16_f32 v83, v143, v145
	v_cvt_pk_bf16_f32 v84, v139, v141
	v_cvt_pk_bf16_f32 v85, v135, v137
	s_nop 0
	v_permlane32_swap_b32_e32 v82, v84
	v_permlane32_swap_b32_e32 v83, v85
	v_add_f32_e32 v78, 0, v164
	v_add_f32_e32 v78, v165, v78
	v_add_f32_e32 v78, v166, v78
	v_add_f32_e32 v78, v168, v78
	v_add_f32_e32 v78, v169, v78
	v_add_f32_e32 v78, v170, v78
	v_add_f32_e32 v78, v154, v78
	v_add_f32_e32 v78, v155, v78
	v_add_f32_e32 v78, v156, v78
	v_add_f32_e32 v78, v157, v78
	v_add_f32_e32 v78, v158, v78
	v_add_f32_e32 v78, v159, v78
	v_add_f32_e32 v78, v160, v78
	v_add_f32_e32 v78, v161, v78
	v_add_f32_e32 v78, v171, v78
	v_add_f32_e32 v78, v172, v78
	v_add_f32_e32 v78, v146, v78
	v_add_f32_e32 v78, v147, v78
	v_add_f32_e32 v78, v148, v78
	v_add_f32_e32 v78, v149, v78
	v_add_f32_e32 v78, v142, v78
	v_add_f32_e32 v78, v143, v78
	v_add_f32_e32 v78, v144, v78
	v_add_f32_e32 v78, v145, v78
	s_waitcnt lgkmcnt(0)
	v_mfma_f32_32x32x16_bf16 v[98:113], v[94:97], v[90:93], v[98:113]
	v_add_f32_e32 v78, v138, v78
	v_add_f32_e32 v78, v139, v78
	v_add_f32_e32 v78, v140, v78
	v_add_f32_e32 v78, v141, v78
	v_add_f32_e32 v78, v134, v78
	v_add_f32_e32 v78, v135, v78
	v_add_f32_e32 v78, v136, v78
	v_add_f32_e32 v78, v137, v78
	v_mov_b32_e32 v79, v78
	s_nop 1
	v_permlane32_swap_b32_e32 v78, v79
	ds_read_b64_tr_b16 v[86:87], v199 offset:0
	ds_read_b64_tr_b16 v[88:89], v199 offset:0x800
	ds_read_b64_tr_b16 v[90:91], v199 offset:0x1000
	ds_read_b64_tr_b16 v[92:93], v199 offset:0x1800
	ds_read_b64_tr_b16 v[94:95], v199 offset:0x2000
	ds_read_b64_tr_b16 v[96:97], v199 offset:0x2800
	ds_read_b64_tr_b16 v[130:131], v199 offset:0x3000
	ds_read_b64_tr_b16 v[132:133], v199 offset:0x3800
	s_waitcnt lgkmcnt(0)
	s_nop 0
	v_mfma_f32_32x32x16_bf16 v[2:17], v[66:69], v[86:89], v[2:17]
	v_max_f32_e32 v80, v115, v115
	v_max_f32_e32 v81, v114, v114
	v_max_f32_e32 v80, v81, v80
	v_max3_f32 v80, v80, v116, v117
	v_max3_f32 v80, v80, v118, v119
	v_max3_f32 v80, v80, v120, v121
	v_max3_f32 v80, v80, v122, v123
	v_mfma_f32_32x32x16_bf16 v[2:17], v[70:73], v[90:93], v[2:17]
	v_max3_f32 v80, v80, v124, v125
	v_max3_f32 v80, v80, v126, v127
	v_max3_f32 v80, v80, v128, v129
	v_max3_f32 v80, v80, v98, v99
	v_max3_f32 v80, v80, v100, v101
	v_max3_f32 v80, v80, v102, v103
	v_max3_f32 v80, v80, v104, v105
	v_mfma_f32_32x32x16_bf16 v[2:17], v[74:77], v[94:97], v[2:17]
	v_max3_f32 v80, v80, v106, v107
	v_max3_f32 v80, v80, v108, v109
	v_max3_f32 v80, v80, v110, v111
	v_max3_f32 v80, v80, v112, v113
	v_mfma_f32_32x32x16_bf16 v[2:17], v[82:85], v[130:133], v[2:17]
	ds_read_b64_tr_b16 v[86:87], v199 offset:0x200
	ds_read_b64_tr_b16 v[88:89], v199 offset:0xa00
	ds_read_b64_tr_b16 v[90:91], v199 offset:0x1200
	ds_read_b64_tr_b16 v[92:93], v199 offset:0x1a00
	ds_read_b64_tr_b16 v[94:95], v199 offset:0x2200
	ds_read_b64_tr_b16 v[96:97], v199 offset:0x2a00
	ds_read_b64_tr_b16 v[130:131], v199 offset:0x3200
	ds_read_b64_tr_b16 v[132:133], v199 offset:0x3a00
	s_waitcnt lgkmcnt(0)
	s_nop 0
	v_mfma_f32_32x32x16_bf16 v[50:65], v[66:69], v[86:89], v[50:65]
	v_mov_b32_e32 v81, v80
	s_nop 1
	v_permlane32_swap_b32_e32 v80, v81
	v_max_f32_e32 v81, v81, v81
	v_max_f32_e32 v80, v80, v80
	v_max_f32_e32 v80, v80, v81
	v_mfma_f32_32x32x16_bf16 v[50:65], v[70:73], v[90:93], v[50:65]
	v_mfma_f32_32x32x16_bf16 v[50:65], v[74:77], v[94:97], v[50:65]
	v_mfma_f32_32x32x16_bf16 v[50:65], v[82:85], v[130:133], v[50:65]
	ds_read_b64_tr_b16 v[86:87], v199 offset:0x400
	ds_read_b64_tr_b16 v[88:89], v199 offset:0xc00
	ds_read_b64_tr_b16 v[90:91], v199 offset:0x1400
	ds_read_b64_tr_b16 v[92:93], v199 offset:0x1c00
	ds_read_b64_tr_b16 v[94:95], v199 offset:0x2400
	ds_read_b64_tr_b16 v[96:97], v199 offset:0x2c00
	ds_read_b64_tr_b16 v[130:131], v199 offset:0x3400
	ds_read_b64_tr_b16 v[132:133], v199 offset:0x3c00
	s_waitcnt lgkmcnt(0)
	s_nop 0
	v_mfma_f32_32x32x16_bf16 v[34:49], v[66:69], v[86:89], v[34:49]
	v_mfma_f32_32x32x16_bf16 v[34:49], v[70:73], v[90:93], v[34:49]
	v_mfma_f32_32x32x16_bf16 v[34:49], v[74:77], v[94:97], v[34:49]
	v_mfma_f32_32x32x16_bf16 v[34:49], v[82:85], v[130:133], v[34:49]
	ds_read_b64_tr_b16 v[86:87], v199 offset:0x600
	ds_read_b64_tr_b16 v[88:89], v199 offset:0xe00
	ds_read_b64_tr_b16 v[90:91], v199 offset:0x1600
	ds_read_b64_tr_b16 v[92:93], v199 offset:0x1e00
	ds_read_b64_tr_b16 v[94:95], v199 offset:0x2600
	ds_read_b64_tr_b16 v[96:97], v199 offset:0x2e00
	ds_read_b64_tr_b16 v[130:131], v199 offset:0x3600
	ds_read_b64_tr_b16 v[132:133], v199 offset:0x3e00
	s_waitcnt lgkmcnt(0)
	s_nop 0
	v_mfma_f32_32x32x16_bf16 v[18:33], v[66:69], v[86:89], v[18:33]
	v_cmp_ge_f32_e32 vcc, s90, v80
	v_mov_b32_e32 v66, 1.0
	s_cmp_eq_u64 vcc, exec
	v_mfma_f32_32x32x16_bf16 v[18:33], v[70:73], v[90:93], v[18:33]
	v_mfma_f32_32x32x16_bf16 v[18:33], v[74:77], v[94:97], v[18:33]
	v_mfma_f32_32x32x16_bf16 v[18:33], v[82:85], v[130:133], v[18:33]
	s_cbranch_scc0 .LBB0_1357

.LBB0_1330:
	v_exp_f32_e32 v68, v114
	v_exp_f32_e32 v69, v98
	v_exp_f32_e32 v70, v115
	v_exp_f32_e32 v80, v99
	v_add_f32_e32 v67, 0, v68
	v_exp_f32_e32 v71, v116
	v_add_f32_e32 v67, v69, v67
	v_exp_f32_e32 v81, v100
	v_add_f32_e32 v67, v70, v67
	v_exp_f32_e32 v72, v117
	v_add_f32_e32 v67, v80, v67
	v_exp_f32_e32 v82, v101
	v_add_f32_e32 v67, v71, v67
	v_exp_f32_e32 v73, v118
	v_add_f32_e32 v67, v81, v67
	v_exp_f32_e32 v83, v102
	v_add_f32_e32 v67, v72, v67
	v_exp_f32_e32 v74, v119
	v_add_f32_e32 v67, v82, v67
	v_exp_f32_e32 v84, v103
	v_add_f32_e32 v67, v73, v67
	v_exp_f32_e32 v75, v120
	v_add_f32_e32 v67, v83, v67
	v_exp_f32_e32 v85, v104
	v_add_f32_e32 v67, v74, v67
	v_exp_f32_e32 v76, v121
	v_add_f32_e32 v67, v84, v67
	v_exp_f32_e32 v86, v105
	v_add_f32_e32 v67, v75, v67
	v_exp_f32_e32 v77, v122
	v_add_f32_e32 v67, v85, v67
	v_exp_f32_e32 v87, v106
	v_add_f32_e32 v67, v76, v67
	v_exp_f32_e32 v88, v123
	v_add_f32_e32 v67, v86, v67
	v_exp_f32_e32 v89, v107
	v_add_f32_e32 v67, v77, v67
	v_exp_f32_e32 v90, v124
	v_add_f32_e32 v67, v87, v67
	v_exp_f32_e32 v91, v108
	v_add_f32_e32 v67, v88, v67
	v_exp_f32_e32 v92, v125
	v_add_f32_e32 v67, v89, v67
	v_exp_f32_e32 v93, v109
	v_add_f32_e32 v67, v90, v67
	v_exp_f32_e32 v94, v126
	v_add_f32_e32 v67, v91, v67
	v_exp_f32_e32 v95, v110
	v_add_f32_e32 v67, v92, v67
	v_exp_f32_e32 v96, v127
	v_add_f32_e32 v67, v93, v67
	v_exp_f32_e32 v97, v111
	v_add_f32_e32 v67, v94, v67
	v_exp_f32_e32 v98, v128
	v_add_f32_e32 v67, v95, v67
	v_exp_f32_e32 v99, v112
	v_add_f32_e32 v67, v96, v67
	v_exp_f32_e32 v100, v129
	v_add_f32_e32 v67, v97, v67
	v_exp_f32_e32 v101, v113
	v_add_f32_e32 v67, v98, v67
	v_add_f32_e32 v67, v99, v67
	v_add_f32_e32 v67, v100, v67
	s_waitcnt vmcnt(0) lgkmcnt(0)
	v_add_f32_e32 v67, v101, v67
	s_waitcnt vmcnt(0)
	s_barrier
	v_cvt_pk_bf16_f32 v70, v68, v70
	v_mov_b32_e32 v68, v67
	v_cvt_pk_bf16_f32 v71, v71, v72
	v_cvt_pk_bf16_f32 v72, v73, v74
	v_cvt_pk_bf16_f32 v73, v75, v76
	v_cvt_pk_bf16_f32 v74, v77, v88
	v_cvt_pk_bf16_f32 v75, v90, v92
	v_cvt_pk_bf16_f32 v76, v94, v96
	v_cvt_pk_bf16_f32 v77, v98, v100
	v_cvt_pk_bf16_f32 v80, v69, v80
	v_cvt_pk_bf16_f32 v81, v81, v82
	v_cvt_pk_bf16_f32 v82, v83, v84
	v_cvt_pk_bf16_f32 v83, v85, v86
	v_cvt_pk_bf16_f32 v84, v87, v89
	v_cvt_pk_bf16_f32 v85, v91, v93
	v_cvt_pk_bf16_f32 v86, v95, v97
	v_cvt_pk_bf16_f32 v87, v99, v101
	s_nop 1
	v_permlane32_swap_b32_e32 v67, v68
	v_permlane32_swap_b32_e32 v70, v72
	v_permlane32_swap_b32_e32 v71, v73
	v_permlane32_swap_b32_e32 v74, v76
	v_permlane32_swap_b32_e32 v75, v77
	v_permlane32_swap_b32_e32 v80, v82
	v_permlane32_swap_b32_e32 v81, v83
	v_permlane32_swap_b32_e32 v84, v86
	v_permlane32_swap_b32_e32 v85, v87
	ds_read_b64_tr_b16 v[88:89], v199 offset:0x4000
	ds_read_b64_tr_b16 v[90:91], v199 offset:0x4800
	ds_read_b64_tr_b16 v[92:93], v199 offset:0x5000
	ds_read_b64_tr_b16 v[94:95], v199 offset:0x5800
	ds_read_b64_tr_b16 v[96:97], v199 offset:0x6000
	ds_read_b64_tr_b16 v[98:99], v199 offset:0x6800
	ds_read_b64_tr_b16 v[100:101], v199 offset:0x7000
	ds_read_b64_tr_b16 v[102:103], v199 offset:0x7800
	s_waitcnt lgkmcnt(0)
	s_nop 0
	v_mfma_f32_32x32x16_bf16 v[2:17], v[70:73], v[88:91], v[2:17]
	v_mfma_f32_32x32x16_bf16 v[2:17], v[74:77], v[92:95], v[2:17]
	v_mfma_f32_32x32x16_bf16 v[2:17], v[80:83], v[96:99], v[2:17]
	v_mfma_f32_32x32x16_bf16 v[2:17], v[84:87], v[100:103], v[2:17]
	ds_read_b64_tr_b16 v[88:89], v199 offset:0x4200
	ds_read_b64_tr_b16 v[90:91], v199 offset:0x4a00
	ds_read_b64_tr_b16 v[92:93], v199 offset:0x5200
	ds_read_b64_tr_b16 v[94:95], v199 offset:0x5a00
	ds_read_b64_tr_b16 v[96:97], v199 offset:0x6200
	ds_read_b64_tr_b16 v[98:99], v199 offset:0x6a00
	ds_read_b64_tr_b16 v[100:101], v199 offset:0x7200
	ds_read_b64_tr_b16 v[102:103], v199 offset:0x7a00
	s_waitcnt lgkmcnt(0)
	s_nop 0
	v_mfma_f32_32x32x16_bf16 v[50:65], v[70:73], v[88:91], v[50:65]
	v_mfma_f32_32x32x16_bf16 v[50:65], v[74:77], v[92:95], v[50:65]
	v_mfma_f32_32x32x16_bf16 v[50:65], v[80:83], v[96:99], v[50:65]
	v_mfma_f32_32x32x16_bf16 v[50:65], v[84:87], v[100:103], v[50:65]
	ds_read_b64_tr_b16 v[88:89], v199 offset:0x4400
	ds_read_b64_tr_b16 v[90:91], v199 offset:0x4c00
	ds_read_b64_tr_b16 v[92:93], v199 offset:0x5400
	ds_read_b64_tr_b16 v[94:95], v199 offset:0x5c00
	ds_read_b64_tr_b16 v[96:97], v199 offset:0x6400
	ds_read_b64_tr_b16 v[98:99], v199 offset:0x6c00
	ds_read_b64_tr_b16 v[100:101], v199 offset:0x7400
	ds_read_b64_tr_b16 v[102:103], v199 offset:0x7c00
	s_waitcnt lgkmcnt(0)
	s_nop 0
	v_mfma_f32_32x32x16_bf16 v[34:49], v[70:73], v[88:91], v[34:49]
	v_mfma_f32_32x32x16_bf16 v[34:49], v[74:77], v[92:95], v[34:49]
	v_mfma_f32_32x32x16_bf16 v[34:49], v[80:83], v[96:99], v[34:49]
	v_mfma_f32_32x32x16_bf16 v[34:49], v[84:87], v[100:103], v[34:49]
	ds_read_b64_tr_b16 v[88:89], v199 offset:0x4600
	ds_read_b64_tr_b16 v[90:91], v199 offset:0x4e00
	ds_read_b64_tr_b16 v[92:93], v199 offset:0x5600
	ds_read_b64_tr_b16 v[94:95], v199 offset:0x5e00
	ds_read_b64_tr_b16 v[96:97], v199 offset:0x6600
	ds_read_b64_tr_b16 v[98:99], v199 offset:0x6e00
	ds_read_b64_tr_b16 v[100:101], v199 offset:0x7600
	ds_read_b64_tr_b16 v[102:103], v199 offset:0x7e00
	s_waitcnt lgkmcnt(0)
	s_nop 0
	v_mfma_f32_32x32x16_bf16 v[18:33], v[70:73], v[88:91], v[18:33]
	v_mfma_f32_32x32x16_bf16 v[18:33], v[74:77], v[92:95], v[18:33]
	v_mfma_f32_32x32x16_bf16 v[18:33], v[80:83], v[96:99], v[18:33]
	v_mfma_f32_32x32x16_bf16 v[18:33], v[84:87], v[100:103], v[18:33]
	s_and_saveexec_b64 s[40:41], s[38:39]
	v_add_f32_e32 v69, v78, v79
	v_fmac_f32_e32 v69, v198, v184
	v_add_f32_e32 v67, v67, v68
	v_fmac_f32_e32 v67, v69, v66
	ds_write_b32 v197, v67
	s_or_b64 exec, exec, s[40:41]
	s_waitcnt lgkmcnt(0)
	v_add_u32_e32 v74, s78, v162
	ds_read_b128 v[66:69], v74
	ds_read_b128 v[70:73], v74 offset:32
	s_lshl_b64 s[38:39], s[76:77], 12
	s_add_u32 s3, s59, s38
	s_addc_u32 s33, s74, s39
	s_waitcnt lgkmcnt(1)
	v_rcp_f32_e32 v75, v66
	s_lshl_b32 s2, s79, 1
	v_rcp_f32_e32 v76, v67
	v_rcp_f32_e32 v77, v68
	v_rcp_f32_e32 v78, v69
	s_waitcnt lgkmcnt(0)
	v_rcp_f32_e32 v79, v70
	ds_read_b128 v[66:69], v74 offset:64
	v_rcp_f32_e32 v80, v71
	v_rcp_f32_e32 v81, v72
	v_rcp_f32_e32 v82, v73
	ds_read_b128 v[70:73], v74 offset:96
	s_add_i32 s2, s2, 0
	v_lshlrev_b32_e32 v74, 10, v196
	v_lshlrev_b32_e32 v83, 1, v195
	v_mul_f32_e32 v2, v2, v75
	s_waitcnt lgkmcnt(0)
	s_barrier
	v_add3_u32 v74, s2, v74, v83
	v_cvt_pk_bf16_f32 v2, v2, v167
	ds_write_b16 v74, v2
	v_mul_f32_e32 v2, v50, v75
	v_cvt_pk_bf16_f32 v2, v2, v167
	ds_write_b16 v74, v2 offset:64
	v_mul_f32_e32 v2, v34, v75
	v_cvt_pk_bf16_f32 v2, v2, v167
	ds_write_b16 v74, v2 offset:128
	v_mul_f32_e32 v2, v18, v75
	v_cvt_pk_bf16_f32 v2, v2, v167
	ds_write_b16 v74, v2 offset:192
	v_mul_f32_e32 v2, v3, v76
	v_cvt_pk_bf16_f32 v2, v2, v167
	ds_write_b16 v74, v2 offset:256
	v_mul_f32_e32 v2, v51, v76
	v_cvt_pk_bf16_f32 v2, v2, v167
	ds_write_b16 v74, v2 offset:320
	v_mul_f32_e32 v2, v35, v76
	v_cvt_pk_bf16_f32 v2, v2, v167
	ds_write_b16 v74, v2 offset:384
	v_mul_f32_e32 v2, v19, v76
	v_cvt_pk_bf16_f32 v2, v2, v167
	ds_write_b16 v74, v2 offset:448
	v_mul_f32_e32 v2, v4, v77
	v_cvt_pk_bf16_f32 v2, v2, v167
	ds_write_b16 v74, v2 offset:512
	v_mul_f32_e32 v2, v52, v77
	v_cvt_pk_bf16_f32 v2, v2, v167
	ds_write_b16 v74, v2 offset:576
	v_mul_f32_e32 v2, v36, v77
	v_cvt_pk_bf16_f32 v2, v2, v167
	ds_write_b16 v74, v2 offset:640
	v_mul_f32_e32 v2, v20, v77
	v_cvt_pk_bf16_f32 v2, v2, v167
	ds_write_b16 v74, v2 offset:704
	v_mul_f32_e32 v2, v5, v78
	v_cvt_pk_bf16_f32 v2, v2, v167
	ds_write_b16 v74, v2 offset:768
	v_mul_f32_e32 v2, v53, v78
	v_cvt_pk_bf16_f32 v2, v2, v167
	ds_write_b16 v74, v2 offset:832
	v_mul_f32_e32 v2, v37, v78
	v_cvt_pk_bf16_f32 v2, v2, v167
	ds_write_b16 v74, v2 offset:896
	v_mul_f32_e32 v2, v21, v78
	v_cvt_pk_bf16_f32 v2, v2, v167
	ds_write_b16 v74, v2 offset:960
	v_mul_f32_e32 v2, v6, v79
	v_cvt_pk_bf16_f32 v2, v2, v167
	ds_write_b16 v74, v2 offset:2048
	v_mul_f32_e32 v2, v54, v79
	v_cvt_pk_bf16_f32 v2, v2, v167
	ds_write_b16 v74, v2 offset:2112
	v_mul_f32_e32 v2, v38, v79
	v_cvt_pk_bf16_f32 v2, v2, v167
	ds_write_b16 v74, v2 offset:2176
	v_mul_f32_e32 v2, v22, v79
	v_cvt_pk_bf16_f32 v2, v2, v167
	ds_write_b16 v74, v2 offset:2240
	v_mul_f32_e32 v2, v7, v80
	v_cvt_pk_bf16_f32 v2, v2, v167
	ds_write_b16 v74, v2 offset:2304
	v_mul_f32_e32 v2, v55, v80
	v_cvt_pk_bf16_f32 v2, v2, v167
	ds_write_b16 v74, v2 offset:2368
	v_mul_f32_e32 v2, v39, v80
	v_cvt_pk_bf16_f32 v2, v2, v167
	ds_write_b16 v74, v2 offset:2432
	v_mul_f32_e32 v2, v23, v80
	v_cvt_pk_bf16_f32 v2, v2, v167
	ds_write_b16 v74, v2 offset:2496
	v_mul_f32_e32 v2, v8, v81
	v_cvt_pk_bf16_f32 v2, v2, v167
	ds_write_b16 v74, v2 offset:2560
	v_mul_f32_e32 v2, v56, v81
	v_cvt_pk_bf16_f32 v2, v2, v167
	ds_write_b16 v74, v2 offset:2624
	v_mul_f32_e32 v2, v40, v81
	v_cvt_pk_bf16_f32 v2, v2, v167
	ds_write_b16 v74, v2 offset:2688
	v_mul_f32_e32 v2, v24, v81
	v_cvt_pk_bf16_f32 v2, v2, v167
	ds_write_b16 v74, v2 offset:2752
	v_mul_f32_e32 v2, v9, v82
	v_cvt_pk_bf16_f32 v2, v2, v167
	ds_write_b16 v74, v2 offset:2816
	v_mul_f32_e32 v2, v57, v82
	v_cvt_pk_bf16_f32 v2, v2, v167
	v_rcp_f32_e32 v66, v66
	ds_write_b16 v74, v2 offset:2880
	v_mul_f32_e32 v2, v41, v82
	v_cvt_pk_bf16_f32 v2, v2, v167
	ds_write_b16 v74, v2 offset:2944
	v_mul_f32_e32 v2, v25, v82
	v_cvt_pk_bf16_f32 v2, v2, v167
	ds_write_b16 v74, v2 offset:3008
	v_mul_f32_e32 v2, v10, v66
	v_cvt_pk_bf16_f32 v2, v2, v167
	ds_write_b16 v74, v2 offset:4096
	v_mul_f32_e32 v2, v58, v66
	v_cvt_pk_bf16_f32 v2, v2, v167
	v_rcp_f32_e32 v67, v67
	ds_write_b16 v74, v2 offset:4160
	v_mul_f32_e32 v2, v42, v66
	v_cvt_pk_bf16_f32 v2, v2, v167
	ds_write_b16 v74, v2 offset:4224
	v_mul_f32_e32 v2, v26, v66
	v_cvt_pk_bf16_f32 v2, v2, v167
	ds_write_b16 v74, v2 offset:4288
	v_mul_f32_e32 v2, v11, v67
	v_cvt_pk_bf16_f32 v2, v2, v167
	ds_write_b16 v74, v2 offset:4352
	v_mul_f32_e32 v2, v59, v67
	v_cvt_pk_bf16_f32 v2, v2, v167
	v_rcp_f32_e32 v68, v68
	ds_write_b16 v74, v2 offset:4416
	v_mul_f32_e32 v2, v43, v67
	v_cvt_pk_bf16_f32 v2, v2, v167
	ds_write_b16 v74, v2 offset:4480
	v_mul_f32_e32 v2, v27, v67
	v_cvt_pk_bf16_f32 v2, v2, v167
	ds_write_b16 v74, v2 offset:4544
	v_mul_f32_e32 v2, v12, v68
	v_cvt_pk_bf16_f32 v2, v2, v167
	ds_write_b16 v74, v2 offset:4608
	v_mul_f32_e32 v2, v60, v68
	v_cvt_pk_bf16_f32 v2, v2, v167
	v_rcp_f32_e32 v69, v69
	ds_write_b16 v74, v2 offset:4672
	v_mul_f32_e32 v2, v44, v68
	v_cvt_pk_bf16_f32 v2, v2, v167
	ds_write_b16 v74, v2 offset:4736
	v_mul_f32_e32 v2, v28, v68
	v_cvt_pk_bf16_f32 v2, v2, v167
	ds_write_b16 v74, v2 offset:4800
	v_mul_f32_e32 v2, v13, v69
	v_cvt_pk_bf16_f32 v2, v2, v167
	ds_write_b16 v74, v2 offset:4864
	v_mul_f32_e32 v2, v61, v69
	v_cvt_pk_bf16_f32 v2, v2, v167
	v_rcp_f32_e32 v70, v70
	ds_write_b16 v74, v2 offset:4928
	v_mul_f32_e32 v2, v45, v69
	v_cvt_pk_bf16_f32 v2, v2, v167
	ds_write_b16 v74, v2 offset:4992
	v_mul_f32_e32 v2, v29, v69
	v_cvt_pk_bf16_f32 v2, v2, v167
	ds_write_b16 v74, v2 offset:5056
	v_mul_f32_e32 v2, v14, v70
	v_cvt_pk_bf16_f32 v2, v2, v167
	ds_write_b16 v74, v2 offset:6144
	v_mul_f32_e32 v2, v62, v70
	v_cvt_pk_bf16_f32 v2, v2, v167
	v_rcp_f32_e32 v71, v71
	ds_write_b16 v74, v2 offset:6208
	v_mul_f32_e32 v2, v46, v70
	v_cvt_pk_bf16_f32 v2, v2, v167
	ds_write_b16 v74, v2 offset:6272
	v_mul_f32_e32 v2, v30, v70
	v_cvt_pk_bf16_f32 v2, v2, v167
	ds_write_b16 v74, v2 offset:6336
	v_mul_f32_e32 v2, v15, v71
	v_cvt_pk_bf16_f32 v2, v2, v167
	ds_write_b16 v74, v2 offset:6400
	v_mul_f32_e32 v2, v63, v71
	v_cvt_pk_bf16_f32 v2, v2, v167
	v_rcp_f32_e32 v72, v72
	ds_write_b16 v74, v2 offset:6464
	v_mul_f32_e32 v2, v47, v71
	v_cvt_pk_bf16_f32 v2, v2, v167
	ds_write_b16 v74, v2 offset:6528
	v_mul_f32_e32 v2, v31, v71
	v_cvt_pk_bf16_f32 v2, v2, v167
	ds_write_b16 v74, v2 offset:6592
	v_mul_f32_e32 v2, v16, v72
	v_cvt_pk_bf16_f32 v2, v2, v167
	ds_write_b16 v74, v2 offset:6656
	v_mul_f32_e32 v2, v64, v72
	v_cvt_pk_bf16_f32 v2, v2, v167
	v_rcp_f32_e32 v73, v73
	ds_write_b16 v74, v2 offset:6720
	v_mul_f32_e32 v2, v48, v72
	v_cvt_pk_bf16_f32 v2, v2, v167
	ds_write_b16 v74, v2 offset:6784
	v_mul_f32_e32 v2, v32, v72
	v_cvt_pk_bf16_f32 v2, v2, v167
	ds_write_b16 v74, v2 offset:6848
	v_mul_f32_e32 v2, v17, v73
	v_cvt_pk_bf16_f32 v2, v2, v167
	ds_write_b16 v74, v2 offset:6912
	v_mul_f32_e32 v2, v65, v73
	v_cvt_pk_bf16_f32 v2, v2, v167
	ds_write_b16 v74, v2 offset:6976
	v_mul_f32_e32 v2, v49, v73
	v_cvt_pk_bf16_f32 v2, v2, v167
	ds_write_b16 v74, v2 offset:7040
	v_mul_f32_e32 v2, v33, v73
	v_and_b32_e32 v166, 0xf0, v163
	v_cvt_pk_bf16_f32 v2, v2, v167
	ds_write_b16 v74, v2 offset:7104
	v_lshrrev_b32_e32 v14, 4, v194
	v_add_u32_e32 v15, s2, v166
	s_waitcnt lgkmcnt(0)
	v_lshl_add_u32 v2, v14, 8, v15
	v_or_b32_e32 v16, 4, v14
	s_lshl_b32 s12, s12, 1
	ds_read_b128 v[2:5], v2
	v_lshl_add_u32 v6, v16, 8, v15
	s_add_u32 s38, s3, s12
	ds_read_b128 v[6:9], v6
	s_addc_u32 s39, s33, 0
	v_lshl_add_u64 v[10:11], s[38:39], 0, v[166:167]
	v_lshlrev_b32_e32 v166, 12, v14
	v_lshl_add_u64 v[12:13], v[10:11], 0, v[166:167]
	v_lshlrev_b32_e32 v166, 12, v16
	s_waitcnt lgkmcnt(1)
	global_store_dwordx4 v[12:13], v[2:5], off
	v_or_b32_e32 v16, 12, v14
	v_mov_b32_e32 v60, v0
	v_lshl_add_u64 v[2:3], v[10:11], 0, v[166:167]
	s_waitcnt lgkmcnt(0)
	global_store_dwordx4 v[2:3], v[6:9], off
	s_lshl_b32 s76, s75, 2
	s_add_i32 s77, s76, 4
	v_or_b32_e32 v6, 8, v14
	v_lshl_add_u32 v2, v6, 8, v15
	ds_read_b128 v[2:5], v2
	v_lshlrev_b32_e32 v166, 12, v6
	v_lshl_add_u32 v6, v16, 8, v15
	ds_read_b128 v[6:9], v6
	v_lshl_add_u64 v[12:13], v[10:11], 0, v[166:167]
	v_lshlrev_b32_e32 v166, 12, v16
	s_waitcnt lgkmcnt(1)
	global_store_dwordx4 v[12:13], v[2:5], off
	v_or_b32_e32 v16, 20, v14
	v_mov_b32_e32 v163, v167
	v_lshl_add_u64 v[2:3], v[10:11], 0, v[166:167]
	s_waitcnt lgkmcnt(0)
	global_store_dwordx4 v[2:3], v[6:9], off
	v_mov_b32_e32 v165, v167
	s_mov_b32 s44, s13
	v_or_b32_e32 v6, 16, v14
	v_lshl_add_u32 v2, v6, 8, v15
	ds_read_b128 v[2:5], v2
	v_lshlrev_b32_e32 v166, 12, v6
	v_lshl_add_u32 v6, v16, 8, v15
	ds_read_b128 v[6:9], v6
	v_lshl_add_u64 v[12:13], v[10:11], 0, v[166:167]
	v_lshlrev_b32_e32 v166, 12, v16
	s_waitcnt lgkmcnt(1)
	global_store_dwordx4 v[12:13], v[2:5], off
	s_mov_b32 s45, s13
	s_mov_b32 s46, s13
	v_lshl_add_u64 v[2:3], v[10:11], 0, v[166:167]
	s_waitcnt lgkmcnt(0)
	global_store_dwordx4 v[2:3], v[6:9], off
	s_mov_b32 s47, s13
	s_mov_b32 s48, s13
	v_or_b32_e32 v6, 24, v14
	v_lshl_add_u32 v2, v6, 8, v15
	v_or_b32_e32 v14, 28, v14
	ds_read_b128 v[2:5], v2
	v_lshlrev_b32_e32 v166, 12, v6
	v_lshl_add_u32 v6, v14, 8, v15
	ds_read_b128 v[6:9], v6
	v_lshl_add_u64 v[12:13], v[10:11], 0, v[166:167]
	v_lshlrev_b32_e32 v166, 12, v14
	s_waitcnt lgkmcnt(1)
	global_store_dwordx4 v[12:13], v[2:5], off
	s_mov_b32 s49, s13
	s_mov_b32 s50, s13
	v_lshl_add_u64 v[2:3], v[10:11], 0, v[166:167]
	s_waitcnt lgkmcnt(0)
	global_store_dwordx4 v[2:3], v[6:9], off
	s_barrier
	s_mov_b32 s51, s13
	v_readfirstlane_b32 s3, v60
	s_ashr_i32 s33, s3, 6
	s_and_b32 s3, s3, 0x3fffffc0
	s_lshl_b32 s3, s3, 2
	s_lshl_b32 s40, s33, 10
	s_add_i32 s56, s3, 0
	s_ashr_i32 s3, s40, 8
	s_and_b32 s38, s3, 0x1ffff0
	s_lshr_b32 s3, s3, 1
	s_and_b32 s3, s3, 4
	s_add_i32 s42, s40, 0x2000
	s_or_b32 s41, s38, s3
	s_ashr_i32 s3, s42, 8
	s_and_b32 s38, s3, 0x1ffff0
	s_lshr_b32 s3, s3, 1
	s_and_b32 s3, s3, 4
	s_or_b32 s43, s38, s3
	s_lshl_b32 s3, s75, 8
	s_lshl_b32 s75, s33, 12
	s_lshl_b32 s2, s33, 5
	s_add_i32 s33, s75, 0
	s_add_i32 s56, s56, 0x14000
	s_add_i32 s33, s33, 0x14800
	s_or_b32 s38, s62, s3
	s_ashr_i32 s39, s2, 31
	s_add_u32 s62, s38, s2
	v_and_b32_e32 v195, 31, v60
	s_addc_u32 s63, s63, s39
	v_or_b32_e32 v18, s62, v195
	v_mov_b32_e32 v19, s63
	v_lshlrev_b64 v[2:3], 11, v[18:19]
	v_bfe_u32 v196, v60, 5, 1
	v_lshl_add_u64 v[2:3], s[18:19], 0, v[2:3]
	s_lshl_b32 s38, s57, 1
	s_mov_b32 s39, s13
	v_lshlrev_b32_e32 v162, 4, v196
	v_lshl_add_u64 v[2:3], v[2:3], 0, s[38:39]
	v_lshl_add_u64 v[14:15], v[2:3], 0, v[162:163]
	global_load_dwordx4 v[2:5], v[14:15], off
	global_load_dwordx4 v[6:9], v[14:15], off offset:32
	global_load_dwordx4 v[10:13], v[14:15], off offset:64
	s_nop 0
	global_load_dwordx4 v[14:17], v[14:15], off offset:96
	v_lshlrev_b64 v[18:19], 12, v[18:19]
	v_lshl_add_u64 v[18:19], s[14:15], 0, v[18:19]
	v_lshl_add_u64 v[18:19], v[18:19], 0, s[12:13]
	v_lshl_add_u64 v[18:19], v[18:19], 0, v[162:163]
	global_load_dwordx4 v[158:161], v[18:19], off
	global_load_dwordx4 v[154:157], v[18:19], off offset:32
	global_load_dwordx4 v[150:153], v[18:19], off offset:64
	global_load_dwordx4 v[146:149], v[18:19], off offset:96
	global_load_dwordx4 v[142:145], v[18:19], off offset:128
	global_load_dwordx4 v[138:141], v[18:19], off offset:160
	global_load_dwordx4 v[134:137], v[18:19], off offset:192
	global_load_dwordx4 v[130:133], v[18:19], off offset:224
	v_and_b32_e32 v194, 63, v60
	v_lshlrev_b32_e32 v99, 4, v194
	v_bfe_u32 v21, v60, 2, 2
	v_lshrrev_b32_e32 v22, 1, v60
	v_and_or_b32 v21, v22, 8, v21
	v_or_b32_e32 v22, s40, v99
	v_ashrrev_i32_e32 v23, 8, v22
	v_and_b32_e32 v20, 0xf0, v99
	v_lshlrev_b32_e32 v24, 4, v23
	s_movk_i32 s38, 0x70
	v_and_b32_e32 v24, 0xf0, v24
	v_xor_b32_e32 v24, v24, v20
	v_lshrrev_b32_e32 v24, 1, v24
	v_lshlrev_b32_e32 v61, 3, v194
	v_lshl_or_b32 v166, v23, 11, v24
	v_or_b32_e32 v23, s41, v21
	v_lshrrev_b32_e32 v24, 4, v22
	v_and_b32_e32 v98, 24, v61
	v_and_b32_e32 v24, 0x60, v24
	v_lshlrev_b32_e32 v23, 11, v23
	v_or3_b32 v23, v23, v24, v98
	v_or_b32_e32 v24, s42, v99
	v_ashrrev_i32_e32 v25, 8, v24
	v_lshlrev_b32_e32 v26, 4, v25
	v_or_b32_e32 v21, s43, v21
	v_lshrrev_b32_e32 v24, 4, v24
	v_and_b32_e32 v26, 0xf0, v26
	v_xor_b32_e32 v20, v26, v20
	v_and_b32_e32 v24, 0x60, v24
	v_lshlrev_b32_e32 v21, 11, v21
	v_lshrrev_b32_e32 v20, 1, v20
	v_or3_b32 v164, v21, v24, v98
	v_ashrrev_i32_e32 v21, 7, v22
	s_add_i32 s57, s40, 0
	v_lshl_or_b32 v20, v25, 11, v20
	v_xor_b32_e32 v22, v21, v60
	v_lshlrev_b32_e32 v18, 6, v21
	v_add_u32_e32 v200, s33, v99
	v_lshlrev_b64 v[50:51], 1, v[166:167]
	s_add_i32 s78, s57, 0x8000
	v_mov_b32_e32 v21, v167
	v_lshlrev_b32_e32 v22, 3, v22
	s_waitcnt vmcnt(11)
	ds_write_b128 v200, v[2:5]
	s_waitcnt vmcnt(10)
	ds_write_b128 v200, v[6:9] offset:1024
	s_waitcnt vmcnt(9)
	ds_write_b128 v200, v[10:13] offset:2048
	s_waitcnt vmcnt(8)
	ds_write_b128 v200, v[14:17] offset:3072
	v_lshl_add_u64 v[4:5], s[68:69], 0, v[50:51]
	s_mov_b32 m0, s78
	v_lshlrev_b64 v[52:53], 1, v[20:21]
	v_and_or_b32 v2, v22, 56, v18
	global_load_lds_dwordx4 v[4:5], off
	v_lshl_add_u64 v[4:5], s[68:69], 0, v[52:53]
	s_add_i32 s68, s57, 0xa000
	v_mov_b32_e32 v3, v167
	s_mov_b32 m0, s68
	v_lshlrev_b64 v[54:55], 1, v[2:3]
	global_load_lds_dwordx4 v[4:5], off
	v_lshl_add_u64 v[2:3], s[66:67], 0, v[54:55]
	s_add_i32 m0, s11, s40
	s_add_i32 s66, s57, 0xc000
	global_load_lds_dwordx4 v[2:3], off
	v_lshl_add_u64 v[2:3], s[70:71], 0, v[50:51]
	s_mov_b32 m0, s66
	s_add_i32 s67, s57, 0xe000
	s_waitcnt vmcnt(0) lgkmcnt(0)
	s_waitcnt vmcnt(0) lgkmcnt(0)
	s_barrier
	global_load_lds_dwordx4 v[2:3], off
	v_lshl_add_u64 v[2:3], s[70:71], 0, v[52:53]
	s_mov_b32 m0, s67
	v_mov_b32_e32 v166, v23
	global_load_lds_dwordx4 v[2:3], off
	v_lshl_add_u64 v[2:3], s[72:73], 0, v[54:55]
	s_add_i32 m0, s10, s40
	v_lshlrev_b64 v[56:57], 1, v[166:167]
	global_load_lds_dwordx4 v[2:3], off
	v_lshl_add_u64 v[2:3], s[22:23], 0, v[56:57]
	s_mov_b32 m0, s57
	v_lshlrev_b64 v[58:59], 1, v[164:165]
	s_add_i32 s69, s57, 0x2000
	v_lshlrev_b32_e32 v163, 4, v60
	global_load_lds_dwordx4 v[2:3], off
	v_lshl_add_u64 v[2:3], s[22:23], 0, v[58:59]
	s_mov_b32 m0, s69
	v_bitop3_b32 v201, v162, v163, s38 bitop3:0x78
	v_lshl_add_u32 v100, v195, 8, 0
	global_load_lds_dwordx4 v[2:3], off
	v_and_b32_e32 v253, 0x80, v163
	v_add3_u32 v38, v100, v201, v253
	v_xor_b32_e32 v250, 0x80, v38
	ds_read_b128 v[2:5], v38 offset:32768
	ds_read_b128 v[6:9], v250 offset:32768
	v_and_b32_e32 v14, 0x70, v163
	v_bitop3_b32 v202, v162, v14, 32 bitop3:0x36
	v_add3_u32 v86, v100, v202, v253
	v_xor_b32_e32 v251, 0x80, v86
	s_waitcnt lgkmcnt(0)
	v_mfma_f32_32x32x16_bf16 v[18:33], v[2:5], v[158:161], 0
	ds_read_b128 v[2:5], v86 offset:32768
	ds_read_b128 v[10:13], v251 offset:32768
	v_bitop3_b32 v203, v162, v14, 64 bitop3:0x36
	v_add3_u32 v90, v100, v203, v253
	v_xor_b32_e32 v252, 0x80, v90
	s_movk_i32 s33, 0x60
	v_bitop3_b32 v204, v162, v14, s33 bitop3:0x36
	ds_read_b128 v[14:17], v252 offset:32768
	s_waitcnt lgkmcnt(0)
	v_mfma_f32_32x32x16_bf16 v[18:33], v[2:5], v[154:157], v[18:33]
	ds_read_b128 v[2:5], v90 offset:32768
	v_add3_u32 v94, v100, v204, v253
	v_xor_b32_e32 v253, 0x80, v94
	v_lshlrev_b32_e32 v101, 7, v195
	s_mov_b32 s40, s13
	s_mov_b32 s41, s13
	s_mov_b32 s42, s13
	s_mov_b32 s43, s13
	s_waitcnt lgkmcnt(0)
	v_mfma_f32_32x32x16_bf16 v[18:33], v[2:5], v[150:153], v[18:33]
	ds_read_b128 v[2:5], v94 offset:32768
	ds_read_b128 v[34:37], v253 offset:32768
	s_mov_b32 s52, s13
	s_mov_b32 s53, s13
	s_mov_b32 s54, s13
	s_mov_b32 s55, s13
	v_lshl_add_u64 v[174:175], s[60:61], 0, v[54:55]
	v_lshl_add_u64 v[176:177], s[24:25], 0, v[50:51]
	s_waitcnt lgkmcnt(0)
	v_mfma_f32_32x32x16_bf16 v[18:33], v[2:5], v[146:149], v[18:33]
	v_lshl_add_u64 v[178:179], s[24:25], 0, v[52:53]
	v_lshl_add_u64 v[180:181], s[24:25], 0, v[56:57]
	v_lshl_add_u64 v[182:183], s[24:25], 0, v[58:59]
	s_mov_b32 s70, 2
	v_add_u32_e32 v214, s10, v101
	v_cmp_gt_u32_e64 s[38:39], 32, v194
	v_lshl_add_u32 v197, v195, 2, s56
	v_mfma_f32_32x32x16_bf16 v[18:33], v[6:9], v[142:145], v[18:33]
	v_mov_b32_e32 v215, 1.0
	v_mov_b32_e32 v198, 0
	s_movk_i32 s10, 0x80
	v_mfma_f32_32x32x16_bf16 v[18:33], v[10:13], v[138:141], v[18:33]
	v_mfma_f32_32x32x16_bf16 v[18:33], v[14:17], v[134:137], v[18:33]
	v_mfma_f32_32x32x16_bf16 v[18:33], v[34:37], v[130:133], v[18:33]
	v_add_u32_e32 v34, s11, v101
	v_add_u32_e32 v205, v34, v201
	ds_read_b128 v[2:5], v205
	ds_read_b128 v[6:9], v200
	ds_read_b128 v[10:13], v205 offset:4096
	ds_read_b128 v[14:17], v200 offset:1024
	v_add_u32_e32 v206, v34, v202
	v_add_u32_e32 v207, v34, v203
	v_add_u32_e32 v208, v34, v204
	s_movk_i32 s11, 0xc0
	s_waitcnt lgkmcnt(0)
	v_mfma_f32_32x32x16_bf16 v[18:33], v[2:5], v[6:9], v[18:33]
	ds_read_b128 v[2:5], v206
	ds_read_b128 v[62:65], v206 offset:4096
	s_waitcnt lgkmcnt(0)
	v_mfma_f32_32x32x16_bf16 v[18:33], v[2:5], v[14:17], v[18:33]
	ds_read_b128 v[2:5], v207
	ds_read_b128 v[66:69], v200 offset:2048
	ds_read_b128 v[70:73], v207 offset:4096
	ds_read_b128 v[74:77], v200 offset:3072
	s_waitcnt lgkmcnt(0)
	v_mfma_f32_32x32x16_bf16 v[18:33], v[2:5], v[66:69], v[18:33]
	ds_read_b128 v[2:5], v208
	ds_read_b128 v[78:81], v208 offset:4096
	s_waitcnt lgkmcnt(0)
	v_mfma_f32_32x32x16_bf16 v[18:33], v[2:5], v[74:77], v[18:33]
	ds_read_b128 v[2:5], v38 offset:40960
	ds_read_b128 v[82:85], v250 offset:40960
	s_waitcnt lgkmcnt(0)
	v_mfma_f32_32x32x16_bf16 v[34:49], v[2:5], v[158:161], 0
	ds_read_b128 v[2:5], v86 offset:40960
	ds_read_b128 v[86:89], v251 offset:40960
	s_waitcnt lgkmcnt(0)
	v_mfma_f32_32x32x16_bf16 v[34:49], v[2:5], v[154:157], v[34:49]
	ds_read_b128 v[2:5], v90 offset:40960
	ds_read_b128 v[90:93], v252 offset:40960
	s_waitcnt lgkmcnt(0)
	v_mfma_f32_32x32x16_bf16 v[34:49], v[2:5], v[150:153], v[34:49]
	ds_read_b128 v[2:5], v94 offset:40960
	ds_read_b128 v[94:97], v253 offset:40960
	s_waitcnt vmcnt(0) lgkmcnt(0)
	s_waitcnt vmcnt(0) lgkmcnt(0)
	s_barrier
	v_mfma_f32_32x32x16_bf16 v[34:49], v[2:5], v[146:149], v[34:49]
	v_lshlrev_b32_e32 v2, 1, v60
	v_and_b32_e32 v2, 32, v2
	v_and_or_b32 v2, v99, s11, v2
	v_and_b32_e32 v3, 0x100, v61
	s_add_i32 s11, s2, s3
	v_or3_b32 v61, v2, v3, v98
	s_cmp_lg_u32 0, -1
	v_mfma_f32_32x32x16_bf16 v[34:49], v[82:85], v[142:145], v[34:49]
	s_cselect_b32 s2, 0, 0
	v_add_u32_e32 v199, s2, v61
	v_mfma_f32_32x32x16_bf16 v[34:49], v[86:89], v[138:141], v[34:49]
	v_mfma_f32_32x32x16_bf16 v[34:49], v[90:93], v[134:137], v[34:49]
	v_mfma_f32_32x32x16_bf16 v[34:49], v[94:97], v[130:133], v[34:49]
	v_mfma_f32_32x32x16_bf16 v[34:49], v[10:13], v[6:9], v[34:49]
	v_mfma_f32_32x32x16_bf16 v[34:49], v[62:65], v[14:17], v[34:49]
	v_max_f32_e32 v62, v19, v19
	v_max_f32_e32 v63, v18, v18
	v_max_f32_e32 v62, v63, v62
	v_max3_f32 v62, v62, v20, v21
	v_max3_f32 v62, v62, v22, v23
	v_max3_f32 v62, v62, v24, v25
	v_max3_f32 v62, v62, v26, v27
	v_mfma_f32_32x32x16_bf16 v[34:49], v[70:73], v[66:69], v[34:49]
	v_max3_f32 v62, v62, v28, v29
	v_max3_f32 v62, v62, v30, v31
	v_max3_f32 v62, v62, v32, v33
	v_mov_b64_e32 v[2:3], s[40:41]
	v_mov_b64_e32 v[16:17], s[54:55]
	v_mov_b64_e32 v[4:5], s[42:43]
	v_mov_b64_e32 v[6:7], s[44:45]
	v_mfma_f32_32x32x16_bf16 v[34:49], v[78:81], v[74:77], v[34:49]
	v_mov_b64_e32 v[8:9], s[46:47]
	v_mov_b64_e32 v[10:11], s[48:49]
	v_mov_b64_e32 v[12:13], s[50:51]
	v_mov_b64_e32 v[14:15], s[52:53]
	s_nop 7
	v_max3_f32 v62, v62, v34, v35
	v_max3_f32 v62, v62, v36, v37
	v_max3_f32 v62, v62, v38, v39
	v_max3_f32 v62, v62, v40, v41
	v_max3_f32 v62, v62, v42, v43
	v_max3_f32 v62, v62, v44, v45
	v_max3_f32 v62, v62, v46, v47
	v_max3_f32 v62, v62, v48, v49
	v_mov_b32_e32 v63, v62
	s_nop 1
	v_permlane32_swap_b32_e32 v62, v63
	v_max_f32_e32 v63, v63, v63
	v_max_f32_e32 v62, v62, v62
	v_max_f32_e32 v213, v62, v63
	v_sub_f32_e32 v66, v18, v213
	v_and_b32_e32 v18, 7, v60
	v_sub_f32_e32 v69, v21, v213
	v_sub_f32_e32 v68, v20, v213
	v_sub_f32_e32 v67, v19, v213
	v_bitop3_b32 v19, v196, v60, 7 bitop3:0x78
	v_bitop3_b32 v20, v196, v18, 2 bitop3:0x36
	v_bitop3_b32 v21, v196, v18, 4 bitop3:0x36
	v_bitop3_b32 v18, v196, v18, 6 bitop3:0x36
	v_lshlrev_b32_e32 v19, 4, v19
	v_lshlrev_b32_e32 v20, 4, v20
	v_lshlrev_b32_e32 v21, 4, v21
	v_lshlrev_b32_e32 v18, 4, v18
	v_sub_f32_e32 v81, v33, v213
	v_sub_f32_e32 v80, v32, v213
	v_sub_f32_e32 v79, v31, v213
	v_sub_f32_e32 v78, v30, v213
	v_sub_f32_e32 v77, v29, v213
	v_sub_f32_e32 v76, v28, v213
	v_sub_f32_e32 v75, v27, v213
	v_sub_f32_e32 v74, v26, v213
	v_sub_f32_e32 v73, v25, v213
	v_sub_f32_e32 v72, v24, v213
	v_sub_f32_e32 v71, v23, v213
	v_sub_f32_e32 v70, v22, v213
	v_sub_f32_e32 v97, v49, v213
	v_sub_f32_e32 v96, v48, v213
	v_sub_f32_e32 v95, v47, v213
	v_sub_f32_e32 v94, v46, v213
	v_sub_f32_e32 v93, v45, v213
	v_sub_f32_e32 v92, v44, v213
	v_sub_f32_e32 v91, v43, v213
	v_sub_f32_e32 v90, v42, v213
	v_sub_f32_e32 v89, v41, v213
	v_sub_f32_e32 v88, v40, v213
	v_sub_f32_e32 v87, v39, v213
	v_sub_f32_e32 v86, v38, v213
	v_sub_f32_e32 v85, v37, v213
	v_sub_f32_e32 v84, v36, v213
	v_sub_f32_e32 v83, v35, v213
	v_sub_f32_e32 v82, v34, v213
	v_lshlrev_b32_e32 v250, 4, v60
	v_and_b32_e32 v250, 0x80, v250
	v_add3_u32 v212, v100, v19, v250
	v_add3_u32 v211, v100, v20, v250
	v_add3_u32 v210, v100, v21, v250
	v_add3_u32 v209, v100, v18, v250
	v_xor_b32_e32 v250, 0x80, v212
	v_xor_b32_e32 v251, 0x80, v211
	v_xor_b32_e32 v252, 0x80, v210
	v_xor_b32_e32 v253, 0x80, v209
	v_mov_b64_e32 v[64:65], v[16:17]
	v_mov_b64_e32 v[48:49], v[16:17]
	v_mov_b64_e32 v[32:33], v[16:17]
	v_mov_b64_e32 v[62:63], v[14:15]
	v_mov_b64_e32 v[60:61], v[12:13]
	v_mov_b64_e32 v[58:59], v[10:11]
	v_mov_b64_e32 v[56:57], v[8:9]
	v_mov_b64_e32 v[54:55], v[6:7]
	v_mov_b64_e32 v[52:53], v[4:5]
	v_mov_b64_e32 v[50:51], v[2:3]
	v_mov_b64_e32 v[46:47], v[14:15]
	v_mov_b64_e32 v[44:45], v[12:13]
	v_mov_b64_e32 v[42:43], v[10:11]
	v_mov_b64_e32 v[40:41], v[8:9]
	v_mov_b64_e32 v[38:39], v[6:7]
	v_mov_b64_e32 v[36:37], v[4:5]
	v_mov_b64_e32 v[34:35], v[2:3]
	v_mov_b64_e32 v[30:31], v[14:15]
	v_mov_b64_e32 v[28:29], v[12:13]
	v_mov_b64_e32 v[26:27], v[10:11]
	v_mov_b64_e32 v[24:25], v[8:9]
	v_mov_b64_e32 v[22:23], v[6:7]
	v_mov_b64_e32 v[20:21], v[4:5]
	v_mov_b64_e32 v[18:19], v[2:3]
.LBB0_1333:
	v_lshl_add_u64 v[184:185], s[0:1], 0, v[176:177]
	s_mov_b32 m0, s78
	v_lshl_add_u64 v[98:99], v[184:185], 0, s[28:29]
	v_lshl_add_u64 v[188:189], s[0:1], 0, v[178:179]
	global_load_lds_dwordx4 v[98:99], off
	v_lshl_add_u64 v[98:99], v[188:189], 0, s[28:29]
	s_mov_b32 m0, s68
	v_lshl_add_u64 v[192:193], s[0:1], 0, v[174:175]
	global_load_lds_dwordx4 v[98:99], off
	v_lshl_add_u64 v[98:99], v[192:193], 0, s[30:31]
	s_add_i32 m0, s57, 0x10000
	v_lshl_add_u64 v[186:187], s[0:1], 0, v[180:181]
	s_add_i32 s40, s57, 0x4000
	global_load_lds_dwordx4 v[98:99], off
	v_lshl_add_u64 v[98:99], v[186:187], 0, s[34:35]
	s_mov_b32 m0, s40
	v_lshl_add_u64 v[190:191], s[0:1], 0, v[182:183]
	s_add_i32 s33, s57, 0x6000
	global_load_lds_dwordx4 v[98:99], off
	v_lshl_add_u64 v[98:99], v[190:191], 0, s[34:35]
	s_mov_b32 m0, s33
	s_nop 0
	global_load_lds_dwordx4 v[98:99], off
	ds_read_b128 v[216:219], v212 offset:49152
	s_sub_i32 s2, s10, 64
	s_cmp_le_i32 s2, s11
	s_cselect_b64 s[2:3], -1, 0
	v_cndmask_b32_e64 v98, v229, -v213, s[2:3]
	v_mov_b32_e32 v99, v98
	v_mov_b32_e32 v100, v98
	v_mov_b32_e32 v101, v98
	v_mov_b32_e32 v102, v98
	v_mov_b32_e32 v103, v98
	v_mov_b32_e32 v104, v98
	v_mov_b32_e32 v105, v98
	v_mov_b32_e32 v106, v98
	v_mov_b32_e32 v107, v98
	v_mov_b32_e32 v108, v98
	v_mov_b32_e32 v109, v98
	v_mov_b32_e32 v110, v98
	v_mov_b32_e32 v111, v98
	v_mov_b32_e32 v112, v98
	v_mov_b32_e32 v113, v98
	ds_read_b128 v[220:223], v212 offset:57344
	ds_read_b128 v[230:233], v211 offset:49152
	s_waitcnt lgkmcnt(0)
	v_mfma_f32_32x32x16_bf16 v[114:129], v[216:219], v[158:161], v[98:113]
	v_exp_f32_e32 v168, v66
	v_exp_f32_e32 v169, v82
	v_mfma_f32_32x32x16_bf16 v[98:113], v[220:223], v[158:161], v[98:113]
	ds_read_b128 v[216:219], v211 offset:57344
	v_exp_f32_e32 v170, v67
	v_exp_f32_e32 v171, v83
	v_mfma_f32_32x32x16_bf16 v[114:129], v[230:233], v[154:157], v[114:129]
	ds_read_b128 v[220:223], v210 offset:49152
	v_exp_f32_e32 v172, v68
	v_exp_f32_e32 v173, v84
	s_waitcnt lgkmcnt(0)
	v_mfma_f32_32x32x16_bf16 v[98:113], v[216:219], v[154:157], v[98:113]
	ds_read_b128 v[230:233], v210 offset:57344
	v_exp_f32_e32 v224, v69
	v_exp_f32_e32 v225, v85
	v_mfma_f32_32x32x16_bf16 v[114:129], v[220:223], v[150:153], v[114:129]
	ds_read_b128 v[66:69], v209 offset:49152
	v_exp_f32_e32 v220, v70
	v_exp_f32_e32 v221, v86
	s_waitcnt lgkmcnt(0)
	v_mfma_f32_32x32x16_bf16 v[98:113], v[230:233], v[150:153], v[98:113]
	ds_read_b128 v[82:85], v209 offset:57344
	v_exp_f32_e32 v222, v71
	v_exp_f32_e32 v223, v87
	v_mfma_f32_32x32x16_bf16 v[114:129], v[66:69], v[146:149], v[114:129]
	ds_read_b128 v[216:219], v250 offset:49152
	v_exp_f32_e32 v230, v72
	v_exp_f32_e32 v231, v88
	s_waitcnt lgkmcnt(0)
	v_mfma_f32_32x32x16_bf16 v[98:113], v[82:85], v[146:149], v[98:113]
	ds_read_b128 v[66:69], v250 offset:57344
	v_exp_f32_e32 v232, v73
	v_exp_f32_e32 v233, v89
	v_mfma_f32_32x32x16_bf16 v[114:129], v[216:219], v[142:145], v[114:129]
	ds_read_b128 v[70:73], v251 offset:49152
	v_exp_f32_e32 v234, v74
	v_exp_f32_e32 v235, v90
	s_waitcnt lgkmcnt(0)
	v_mfma_f32_32x32x16_bf16 v[98:113], v[66:69], v[142:145], v[98:113]
	ds_read_b128 v[82:85], v251 offset:57344
	v_exp_f32_e32 v236, v75
	v_exp_f32_e32 v237, v91
	v_mfma_f32_32x32x16_bf16 v[114:129], v[70:73], v[138:141], v[114:129]
	ds_read_b128 v[66:69], v252 offset:49152
	v_exp_f32_e32 v238, v76
	v_exp_f32_e32 v239, v92
	s_waitcnt lgkmcnt(0)
	v_mfma_f32_32x32x16_bf16 v[98:113], v[82:85], v[138:141], v[98:113]
	ds_read_b128 v[70:73], v252 offset:57344
	v_exp_f32_e32 v240, v77
	v_exp_f32_e32 v241, v93
	v_mfma_f32_32x32x16_bf16 v[114:129], v[66:69], v[134:137], v[114:129]
	ds_read_b128 v[74:77], v253 offset:49152
	v_exp_f32_e32 v242, v78
	v_exp_f32_e32 v243, v94
	s_waitcnt lgkmcnt(0)
	v_mfma_f32_32x32x16_bf16 v[98:113], v[70:73], v[134:137], v[98:113]
	ds_read_b128 v[66:69], v253 offset:57344
	v_exp_f32_e32 v244, v79
	v_exp_f32_e32 v245, v95
	v_mfma_f32_32x32x16_bf16 v[114:129], v[74:77], v[130:133], v[114:129]
	v_add_u32_e32 v219, v214, v201
	ds_read_b128 v[70:73], v219
	ds_read_b128 v[82:85], v200
	v_exp_f32_e32 v246, v80
	v_exp_f32_e32 v247, v96
	s_waitcnt lgkmcnt(0)
	v_mfma_f32_32x32x16_bf16 v[98:113], v[66:69], v[130:133], v[98:113]
	ds_read_b128 v[74:77], v219 offset:4096
	v_exp_f32_e32 v248, v81
	v_exp_f32_e32 v249, v97
	v_mfma_f32_32x32x16_bf16 v[114:129], v[70:73], v[82:85], v[114:129]
	v_add_u32_e32 v216, v214, v202
	ds_read_b128 v[78:81], v216
	ds_read_b128 v[86:89], v200 offset:1024
	v_cvt_pk_bf16_f32 v66, v168, v170
	v_cvt_pk_bf16_f32 v67, v172, v224
	v_cvt_pk_bf16_f32 v68, v220, v222
	v_cvt_pk_bf16_f32 v69, v230, v232
	s_nop 0
	v_permlane32_swap_b32_e32 v66, v68
	v_permlane32_swap_b32_e32 v67, v69
	s_waitcnt lgkmcnt(0)
	v_mfma_f32_32x32x16_bf16 v[98:113], v[74:77], v[82:85], v[98:113]
	ds_read_b128 v[90:93], v216 offset:4096
	v_mfma_f32_32x32x16_bf16 v[114:129], v[78:81], v[86:89], v[114:129]
	v_add_u32_e32 v217, v214, v203
	ds_read_b128 v[74:77], v217
	ds_read_b128 v[82:85], v200 offset:2048
	v_cvt_pk_bf16_f32 v70, v234, v236
	v_cvt_pk_bf16_f32 v71, v238, v240
	v_cvt_pk_bf16_f32 v72, v242, v244
	v_cvt_pk_bf16_f32 v73, v246, v248
	s_nop 0
	v_permlane32_swap_b32_e32 v70, v72
	v_permlane32_swap_b32_e32 v71, v73
	s_waitcnt lgkmcnt(0)
	v_mfma_f32_32x32x16_bf16 v[98:113], v[90:93], v[86:89], v[98:113]
	ds_read_b128 v[78:81], v217 offset:4096
	v_mfma_f32_32x32x16_bf16 v[114:129], v[74:77], v[82:85], v[114:129]
	v_add_u32_e32 v218, v214, v204
	ds_read_b128 v[86:89], v218
	ds_read_b128 v[90:93], v200 offset:3072
	v_cvt_pk_bf16_f32 v74, v169, v171
	v_cvt_pk_bf16_f32 v75, v173, v225
	v_cvt_pk_bf16_f32 v76, v221, v223
	v_cvt_pk_bf16_f32 v77, v231, v233
	s_nop 0
	v_permlane32_swap_b32_e32 v74, v76
	v_permlane32_swap_b32_e32 v75, v77
	s_waitcnt lgkmcnt(0)
	v_mfma_f32_32x32x16_bf16 v[98:113], v[78:81], v[82:85], v[98:113]
	ds_read_b128 v[94:97], v218 offset:4096
	v_mfma_f32_32x32x16_bf16 v[114:129], v[86:89], v[90:93], v[114:129]
	v_cvt_pk_bf16_f32 v80, v235, v237
	v_cvt_pk_bf16_f32 v81, v239, v241
	v_cvt_pk_bf16_f32 v82, v243, v245
	v_cvt_pk_bf16_f32 v83, v247, v249
	s_nop 0
	v_permlane32_swap_b32_e32 v80, v82
	v_permlane32_swap_b32_e32 v81, v83
	v_add_f32_e32 v78, 0, v168
	v_add_f32_e32 v78, v78, v169
	v_add_f32_e32 v78, v170, v78
	v_add_f32_e32 v78, v171, v78
	v_add_f32_e32 v78, v172, v78
	v_add_f32_e32 v78, v173, v78
	v_add_f32_e32 v78, v224, v78
	v_add_f32_e32 v78, v225, v78
	v_add_f32_e32 v78, v220, v78
	v_add_f32_e32 v78, v221, v78
	v_add_f32_e32 v78, v222, v78
	v_add_f32_e32 v78, v223, v78
	v_add_f32_e32 v78, v230, v78
	v_add_f32_e32 v78, v231, v78
	v_add_f32_e32 v78, v232, v78
	v_add_f32_e32 v78, v233, v78
	v_add_f32_e32 v78, v234, v78
	v_add_f32_e32 v78, v235, v78
	v_add_f32_e32 v78, v236, v78
	v_add_f32_e32 v78, v237, v78
	v_add_f32_e32 v78, v238, v78
	v_add_f32_e32 v78, v239, v78
	v_add_f32_e32 v78, v240, v78
	v_add_f32_e32 v78, v241, v78
	s_waitcnt lgkmcnt(0)
	v_mfma_f32_32x32x16_bf16 v[98:113], v[94:97], v[90:93], v[98:113]
	v_add_f32_e32 v78, v242, v78
	v_add_f32_e32 v78, v243, v78
	v_add_f32_e32 v78, v244, v78
	v_add_f32_e32 v78, v245, v78
	v_add_f32_e32 v78, v246, v78
	v_add_f32_e32 v78, v247, v78
	v_add_f32_e32 v78, v248, v78
	v_add_f32_e32 v220, v249, v78
	v_mov_b32_e32 v221, v220
	s_nop 1
	v_permlane32_swap_b32_e32 v220, v221
	ds_read_b64_tr_b16 v[84:85], v199 offset:0
	ds_read_b64_tr_b16 v[86:87], v199 offset:0x800
	ds_read_b64_tr_b16 v[88:89], v199 offset:0x1000
	ds_read_b64_tr_b16 v[90:91], v199 offset:0x1800
	ds_read_b64_tr_b16 v[92:93], v199 offset:0x2000
	ds_read_b64_tr_b16 v[94:95], v199 offset:0x2800
	ds_read_b64_tr_b16 v[222:223], v199 offset:0x3000
	ds_read_b64_tr_b16 v[224:225], v199 offset:0x3800
	s_waitcnt lgkmcnt(0)
	s_nop 0
	v_mfma_f32_32x32x16_bf16 v[2:17], v[66:69], v[84:87], v[2:17]
	v_max_f32_e32 v78, v115, v115
	v_max_f32_e32 v79, v114, v114
	v_max_f32_e32 v78, v79, v78
	v_max3_f32 v78, v78, v116, v117
	v_max3_f32 v78, v78, v118, v119
	v_max3_f32 v78, v78, v120, v121
	v_max3_f32 v78, v78, v122, v123
	v_mfma_f32_32x32x16_bf16 v[2:17], v[70:73], v[88:91], v[2:17]
	v_max3_f32 v78, v78, v124, v125
	v_max3_f32 v78, v78, v126, v127
	v_max3_f32 v78, v78, v128, v129
	v_max3_f32 v78, v78, v98, v99
	v_max3_f32 v78, v78, v100, v101
	v_max3_f32 v78, v78, v102, v103
	v_max3_f32 v78, v78, v104, v105
	v_mfma_f32_32x32x16_bf16 v[2:17], v[74:77], v[92:95], v[2:17]
	v_max3_f32 v78, v78, v106, v107
	v_max3_f32 v78, v78, v108, v109
	v_max3_f32 v78, v78, v110, v111
	v_max3_f32 v78, v78, v112, v113
	v_mfma_f32_32x32x16_bf16 v[2:17], v[80:83], v[222:225], v[2:17]
	ds_read_b64_tr_b16 v[84:85], v199 offset:0x200
	ds_read_b64_tr_b16 v[86:87], v199 offset:0xa00
	ds_read_b64_tr_b16 v[88:89], v199 offset:0x1200
	ds_read_b64_tr_b16 v[90:91], v199 offset:0x1a00
	ds_read_b64_tr_b16 v[92:93], v199 offset:0x2200
	ds_read_b64_tr_b16 v[94:95], v199 offset:0x2a00
	ds_read_b64_tr_b16 v[222:223], v199 offset:0x3200
	ds_read_b64_tr_b16 v[224:225], v199 offset:0x3a00
	s_waitcnt lgkmcnt(0)
	s_nop 0
	v_mfma_f32_32x32x16_bf16 v[50:65], v[66:69], v[84:87], v[50:65]
	v_mov_b32_e32 v79, v78
	s_nop 1
	v_permlane32_swap_b32_e32 v78, v79
	v_max_f32_e32 v79, v79, v79
	v_max_f32_e32 v78, v78, v78
	v_max_f32_e32 v78, v78, v79
	v_mfma_f32_32x32x16_bf16 v[50:65], v[70:73], v[88:91], v[50:65]
	v_mfma_f32_32x32x16_bf16 v[50:65], v[74:77], v[92:95], v[50:65]
	v_mfma_f32_32x32x16_bf16 v[50:65], v[80:83], v[222:225], v[50:65]
	ds_read_b64_tr_b16 v[84:85], v199 offset:0x400
	ds_read_b64_tr_b16 v[86:87], v199 offset:0xc00
	ds_read_b64_tr_b16 v[88:89], v199 offset:0x1400
	ds_read_b64_tr_b16 v[90:91], v199 offset:0x1c00
	ds_read_b64_tr_b16 v[92:93], v199 offset:0x2400
	ds_read_b64_tr_b16 v[94:95], v199 offset:0x2c00
	ds_read_b64_tr_b16 v[222:223], v199 offset:0x3400
	ds_read_b64_tr_b16 v[224:225], v199 offset:0x3c00
	s_waitcnt lgkmcnt(0)
	s_nop 0
	v_mfma_f32_32x32x16_bf16 v[34:49], v[66:69], v[84:87], v[34:49]
	v_mfma_f32_32x32x16_bf16 v[34:49], v[70:73], v[88:91], v[34:49]
	v_mfma_f32_32x32x16_bf16 v[34:49], v[74:77], v[92:95], v[34:49]
	v_mfma_f32_32x32x16_bf16 v[34:49], v[80:83], v[222:225], v[34:49]
	ds_read_b64_tr_b16 v[84:85], v199 offset:0x600
	ds_read_b64_tr_b16 v[86:87], v199 offset:0xe00
	ds_read_b64_tr_b16 v[88:89], v199 offset:0x1600
	ds_read_b64_tr_b16 v[90:91], v199 offset:0x1e00
	ds_read_b64_tr_b16 v[92:93], v199 offset:0x2600
	ds_read_b64_tr_b16 v[94:95], v199 offset:0x2e00
	ds_read_b64_tr_b16 v[222:223], v199 offset:0x3600
	ds_read_b64_tr_b16 v[224:225], v199 offset:0x3e00
	s_waitcnt lgkmcnt(0)
	s_nop 0
	v_mfma_f32_32x32x16_bf16 v[18:33], v[66:69], v[84:87], v[18:33]
	v_cmp_ge_f32_e32 vcc, s90, v78
	s_cmp_eq_u64 vcc, exec
	v_mfma_f32_32x32x16_bf16 v[18:33], v[70:73], v[88:91], v[18:33]
	v_mfma_f32_32x32x16_bf16 v[18:33], v[74:77], v[92:95], v[18:33]
	v_mfma_f32_32x32x16_bf16 v[18:33], v[80:83], v[222:225], v[18:33]
	s_cbranch_scc0 .LBB0_1348
	v_mov_b32_e32 v222, 1.0

.LBB0_1341:
	s_mov_b32 m0, s57
	v_lshl_add_u64 v[66:67], v[186:187], 0, s[36:37]
	global_load_lds_dwordx4 v[66:67], off
	v_lshl_add_u64 v[66:67], v[190:191], 0, s[36:37]
	s_mov_b32 m0, s69
	s_nop 0
	global_load_lds_dwordx4 v[66:67], off
	ds_read_b128 v[184:187], v212 offset:32768
	s_cmp_le_i32 s10, s11
	s_cselect_b64 s[2:3], -1, 0
	v_cndmask_b32_e64 v82, v229, -v213, s[2:3]
	v_mov_b32_e32 v83, v82
	v_mov_b32_e32 v84, v82
	v_mov_b32_e32 v85, v82
	v_mov_b32_e32 v86, v82
	v_mov_b32_e32 v87, v82
	v_mov_b32_e32 v88, v82
	v_mov_b32_e32 v89, v82
	v_mov_b32_e32 v90, v82
	v_mov_b32_e32 v91, v82
	v_mov_b32_e32 v92, v82
	v_mov_b32_e32 v93, v82
	v_mov_b32_e32 v94, v82
	v_mov_b32_e32 v95, v82
	v_mov_b32_e32 v96, v82
	v_mov_b32_e32 v97, v82
	ds_read_b128 v[188:191], v212 offset:40960
	ds_read_b128 v[230:233], v211 offset:32768
	s_waitcnt lgkmcnt(0)
	v_mfma_f32_32x32x16_bf16 v[66:81], v[184:187], v[158:161], v[82:97]
	v_exp_f32_e32 v168, v114
	v_exp_f32_e32 v169, v98
	v_mfma_f32_32x32x16_bf16 v[82:97], v[188:191], v[158:161], v[82:97]
	ds_read_b128 v[184:187], v211 offset:40960
	v_exp_f32_e32 v170, v115
	v_exp_f32_e32 v171, v99
	v_mfma_f32_32x32x16_bf16 v[66:81], v[230:233], v[154:157], v[66:81]
	ds_read_b128 v[188:191], v210 offset:32768
	v_exp_f32_e32 v172, v116
	v_exp_f32_e32 v173, v100
	s_waitcnt lgkmcnt(0)
	v_mfma_f32_32x32x16_bf16 v[82:97], v[184:187], v[154:157], v[82:97]
	ds_read_b128 v[230:233], v210 offset:40960
	v_exp_f32_e32 v192, v117
	v_exp_f32_e32 v193, v101
	v_mfma_f32_32x32x16_bf16 v[66:81], v[188:191], v[150:153], v[66:81]
	ds_read_b128 v[98:101], v209 offset:32768
	v_exp_f32_e32 v188, v118
	v_exp_f32_e32 v189, v102
	s_waitcnt lgkmcnt(0)
	v_mfma_f32_32x32x16_bf16 v[82:97], v[230:233], v[150:153], v[82:97]
	ds_read_b128 v[114:117], v209 offset:40960
	v_exp_f32_e32 v190, v119
	v_exp_f32_e32 v191, v103
	v_mfma_f32_32x32x16_bf16 v[66:81], v[98:101], v[146:149], v[66:81]
	ds_read_b128 v[184:187], v250 offset:32768
	v_exp_f32_e32 v223, v120
	v_exp_f32_e32 v224, v104
	s_waitcnt lgkmcnt(0)
	v_mfma_f32_32x32x16_bf16 v[82:97], v[114:117], v[146:149], v[82:97]
	ds_read_b128 v[98:101], v250 offset:40960
	v_exp_f32_e32 v225, v121
	v_exp_f32_e32 v230, v105
	v_mfma_f32_32x32x16_bf16 v[66:81], v[184:187], v[142:145], v[66:81]
	ds_read_b128 v[102:105], v251 offset:32768
	v_exp_f32_e32 v184, v122
	v_exp_f32_e32 v185, v106
	s_waitcnt lgkmcnt(0)
	v_mfma_f32_32x32x16_bf16 v[82:97], v[98:101], v[142:145], v[82:97]
	ds_read_b128 v[114:117], v251 offset:40960
	v_exp_f32_e32 v186, v123
	v_exp_f32_e32 v187, v107
	v_mfma_f32_32x32x16_bf16 v[66:81], v[102:105], v[138:141], v[66:81]
	ds_read_b128 v[98:101], v252 offset:32768
	v_exp_f32_e32 v231, v124
	v_exp_f32_e32 v232, v108
	s_waitcnt lgkmcnt(0)
	v_mfma_f32_32x32x16_bf16 v[82:97], v[114:117], v[138:141], v[82:97]
	ds_read_b128 v[102:105], v252 offset:40960
	v_exp_f32_e32 v233, v125
	v_exp_f32_e32 v234, v109
	v_mfma_f32_32x32x16_bf16 v[66:81], v[98:101], v[134:137], v[66:81]
	ds_read_b128 v[106:109], v253 offset:32768
	v_exp_f32_e32 v235, v126
	v_exp_f32_e32 v236, v110
	s_waitcnt lgkmcnt(0)
	v_mfma_f32_32x32x16_bf16 v[82:97], v[102:105], v[134:137], v[82:97]
	ds_read_b128 v[98:101], v253 offset:40960
	v_exp_f32_e32 v237, v127
	v_exp_f32_e32 v238, v111
	v_mfma_f32_32x32x16_bf16 v[66:81], v[106:109], v[130:133], v[66:81]
	ds_read_b128 v[102:105], v205
	ds_read_b128 v[114:117], v200
	v_exp_f32_e32 v239, v128
	v_exp_f32_e32 v240, v112
	s_waitcnt lgkmcnt(0)
	v_mfma_f32_32x32x16_bf16 v[82:97], v[98:101], v[130:133], v[82:97]
	ds_read_b128 v[106:109], v205 offset:4096
	v_exp_f32_e32 v241, v129
	v_exp_f32_e32 v242, v113
	v_mfma_f32_32x32x16_bf16 v[66:81], v[102:105], v[114:117], v[66:81]
	ds_read_b128 v[110:113], v206
	ds_read_b128 v[118:121], v200 offset:1024
	v_cvt_pk_bf16_f32 v98, v168, v170
	v_cvt_pk_bf16_f32 v99, v172, v192
	v_cvt_pk_bf16_f32 v100, v188, v190
	v_cvt_pk_bf16_f32 v101, v223, v225
	s_nop 0
	v_permlane32_swap_b32_e32 v98, v100
	v_permlane32_swap_b32_e32 v99, v101
	s_waitcnt lgkmcnt(0)
	v_mfma_f32_32x32x16_bf16 v[82:97], v[106:109], v[114:117], v[82:97]
	ds_read_b128 v[122:125], v206 offset:4096
	v_mfma_f32_32x32x16_bf16 v[66:81], v[110:113], v[118:121], v[66:81]
	ds_read_b128 v[106:109], v207
	ds_read_b128 v[114:117], v200 offset:2048
	v_cvt_pk_bf16_f32 v102, v184, v186
	v_cvt_pk_bf16_f32 v103, v231, v233
	v_cvt_pk_bf16_f32 v104, v235, v237
	v_cvt_pk_bf16_f32 v105, v239, v241
	s_nop 0
	v_permlane32_swap_b32_e32 v102, v104
	v_permlane32_swap_b32_e32 v103, v105
	s_waitcnt lgkmcnt(0)
	v_mfma_f32_32x32x16_bf16 v[82:97], v[122:125], v[118:121], v[82:97]
	ds_read_b128 v[110:113], v207 offset:4096
	v_mfma_f32_32x32x16_bf16 v[66:81], v[106:109], v[114:117], v[66:81]
	ds_read_b128 v[118:121], v208
	ds_read_b128 v[122:125], v200 offset:3072
	v_cvt_pk_bf16_f32 v106, v169, v171
	v_cvt_pk_bf16_f32 v107, v173, v193
	v_cvt_pk_bf16_f32 v108, v189, v191
	v_cvt_pk_bf16_f32 v109, v224, v230
	s_nop 0
	v_permlane32_swap_b32_e32 v106, v108
	v_permlane32_swap_b32_e32 v107, v109
	s_waitcnt lgkmcnt(0)
	v_mfma_f32_32x32x16_bf16 v[82:97], v[110:113], v[114:117], v[82:97]
	ds_read_b128 v[126:129], v208 offset:4096
	v_mfma_f32_32x32x16_bf16 v[66:81], v[118:121], v[122:125], v[66:81]
	v_cvt_pk_bf16_f32 v114, v185, v187
	v_cvt_pk_bf16_f32 v115, v232, v234
	v_cvt_pk_bf16_f32 v116, v236, v238
	v_cvt_pk_bf16_f32 v117, v240, v242
	s_nop 0
	v_permlane32_swap_b32_e32 v114, v116
	v_permlane32_swap_b32_e32 v115, v117
	v_add_f32_e32 v110, 0, v168
	v_add_f32_e32 v110, v169, v110
	v_add_f32_e32 v110, v170, v110
	v_add_f32_e32 v110, v171, v110
	v_add_f32_e32 v110, v172, v110
	v_add_f32_e32 v110, v173, v110
	v_add_f32_e32 v110, v192, v110
	v_add_f32_e32 v110, v193, v110
	v_add_f32_e32 v110, v188, v110
	v_add_f32_e32 v110, v189, v110
	v_add_f32_e32 v110, v190, v110
	v_add_f32_e32 v110, v191, v110
	v_add_f32_e32 v110, v223, v110
	v_add_f32_e32 v110, v224, v110
	v_add_f32_e32 v110, v225, v110
	v_add_f32_e32 v110, v230, v110
	v_add_f32_e32 v110, v184, v110
	v_add_f32_e32 v110, v185, v110
	v_add_f32_e32 v110, v186, v110
	v_add_f32_e32 v110, v187, v110
	v_add_f32_e32 v110, v231, v110
	v_add_f32_e32 v110, v232, v110
	v_add_f32_e32 v110, v233, v110
	v_add_f32_e32 v110, v234, v110
	s_waitcnt lgkmcnt(0)
	v_mfma_f32_32x32x16_bf16 v[82:97], v[126:129], v[122:125], v[82:97]
	v_add_f32_e32 v110, v235, v110
	v_add_f32_e32 v110, v236, v110
	v_add_f32_e32 v110, v237, v110
	v_add_f32_e32 v110, v238, v110
	v_add_f32_e32 v110, v239, v110
	v_add_f32_e32 v110, v240, v110
	v_add_f32_e32 v110, v241, v110
	v_add_f32_e32 v110, v242, v110
	v_mov_b32_e32 v111, v110
	s_nop 1
	v_permlane32_swap_b32_e32 v110, v111
	ds_read_b64_tr_b16 v[118:119], v199 offset:0x4000
	ds_read_b64_tr_b16 v[120:121], v199 offset:0x4800
	ds_read_b64_tr_b16 v[122:123], v199 offset:0x5000
	ds_read_b64_tr_b16 v[124:125], v199 offset:0x5800
	ds_read_b64_tr_b16 v[126:127], v199 offset:0x6000
	ds_read_b64_tr_b16 v[128:129], v199 offset:0x6800
	ds_read_b64_tr_b16 v[184:185], v199 offset:0x7000
	ds_read_b64_tr_b16 v[186:187], v199 offset:0x7800
	s_waitcnt lgkmcnt(0)
	s_nop 0
	v_mfma_f32_32x32x16_bf16 v[2:17], v[98:101], v[118:121], v[2:17]
	v_max_f32_e32 v112, v67, v67
	v_max_f32_e32 v113, v66, v66
	v_max_f32_e32 v112, v113, v112
	v_max3_f32 v112, v112, v68, v69
	v_max3_f32 v112, v112, v70, v71
	v_max3_f32 v112, v112, v72, v73
	v_max3_f32 v112, v112, v74, v75
	v_mfma_f32_32x32x16_bf16 v[2:17], v[102:105], v[122:125], v[2:17]
	v_max3_f32 v112, v112, v76, v77
	v_max3_f32 v112, v112, v78, v79
	v_max3_f32 v112, v112, v80, v81
	v_max3_f32 v112, v112, v82, v83
	v_max3_f32 v112, v112, v84, v85
	v_max3_f32 v112, v112, v86, v87
	v_max3_f32 v112, v112, v88, v89
	v_mfma_f32_32x32x16_bf16 v[2:17], v[106:109], v[126:129], v[2:17]
	v_max3_f32 v112, v112, v90, v91
	v_max3_f32 v112, v112, v92, v93
	v_max3_f32 v112, v112, v94, v95
	v_max3_f32 v112, v112, v96, v97
	v_mfma_f32_32x32x16_bf16 v[2:17], v[114:117], v[184:187], v[2:17]
	ds_read_b64_tr_b16 v[118:119], v199 offset:0x4200
	ds_read_b64_tr_b16 v[120:121], v199 offset:0x4a00
	ds_read_b64_tr_b16 v[122:123], v199 offset:0x5200
	ds_read_b64_tr_b16 v[124:125], v199 offset:0x5a00
	ds_read_b64_tr_b16 v[126:127], v199 offset:0x6200
	ds_read_b64_tr_b16 v[128:129], v199 offset:0x6a00
	ds_read_b64_tr_b16 v[184:185], v199 offset:0x7200
	ds_read_b64_tr_b16 v[186:187], v199 offset:0x7a00
	s_waitcnt lgkmcnt(0)
	s_nop 0
	v_mfma_f32_32x32x16_bf16 v[50:65], v[98:101], v[118:121], v[50:65]
	v_mov_b32_e32 v113, v112
	s_nop 1
	v_permlane32_swap_b32_e32 v112, v113
	v_max_f32_e32 v113, v113, v113
	v_max_f32_e32 v112, v112, v112
	v_max_f32_e32 v112, v112, v113
	v_mfma_f32_32x32x16_bf16 v[50:65], v[102:105], v[122:125], v[50:65]
	v_mfma_f32_32x32x16_bf16 v[50:65], v[106:109], v[126:129], v[50:65]
	v_mfma_f32_32x32x16_bf16 v[50:65], v[114:117], v[184:187], v[50:65]
	ds_read_b64_tr_b16 v[118:119], v199 offset:0x4400
	ds_read_b64_tr_b16 v[120:121], v199 offset:0x4c00
	ds_read_b64_tr_b16 v[122:123], v199 offset:0x5400
	ds_read_b64_tr_b16 v[124:125], v199 offset:0x5c00
	ds_read_b64_tr_b16 v[126:127], v199 offset:0x6400
	ds_read_b64_tr_b16 v[128:129], v199 offset:0x6c00
	ds_read_b64_tr_b16 v[184:185], v199 offset:0x7400
	ds_read_b64_tr_b16 v[186:187], v199 offset:0x7c00
	s_waitcnt lgkmcnt(0)
	s_nop 0
	v_mfma_f32_32x32x16_bf16 v[34:49], v[98:101], v[118:121], v[34:49]
	v_mfma_f32_32x32x16_bf16 v[34:49], v[102:105], v[122:125], v[34:49]
	v_mfma_f32_32x32x16_bf16 v[34:49], v[106:109], v[126:129], v[34:49]
	v_mfma_f32_32x32x16_bf16 v[34:49], v[114:117], v[184:187], v[34:49]
	ds_read_b64_tr_b16 v[118:119], v199 offset:0x4600
	ds_read_b64_tr_b16 v[120:121], v199 offset:0x4e00
	ds_read_b64_tr_b16 v[122:123], v199 offset:0x5600
	ds_read_b64_tr_b16 v[124:125], v199 offset:0x5e00
	ds_read_b64_tr_b16 v[126:127], v199 offset:0x6600
	ds_read_b64_tr_b16 v[128:129], v199 offset:0x6e00
	ds_read_b64_tr_b16 v[186:187], v199 offset:0x7600
	ds_read_b64_tr_b16 v[188:189], v199 offset:0x7e00
	s_waitcnt lgkmcnt(0)
	s_nop 0
	v_mfma_f32_32x32x16_bf16 v[18:33], v[98:101], v[118:121], v[18:33]
	v_cmp_ge_f32_e32 vcc, s90, v112
	v_mov_b32_e32 v184, 1.0
	s_cmp_eq_u64 vcc, exec
	v_mfma_f32_32x32x16_bf16 v[18:33], v[102:105], v[122:125], v[18:33]
	v_mfma_f32_32x32x16_bf16 v[18:33], v[106:109], v[126:129], v[18:33]
	v_mfma_f32_32x32x16_bf16 v[18:33], v[114:117], v[186:189], v[18:33]
	s_cbranch_scc0 .LBB0_1349

.LBB0_1350:
	s_or_b32 s10, s76, 3
	s_lshl_b32 s2, s10, 18
	s_add_u32 s2, s22, s2
	s_addc_u32 s3, s23, 0
	s_mov_b32 m0, s40
	v_lshl_add_u64 v[98:99], v[166:167], 1, s[2:3]
	global_load_lds_dwordx4 v[98:99], off
	v_lshl_add_u64 v[98:99], v[164:165], 1, s[2:3]
	s_mov_b32 m0, s33
	s_nop 0
	global_load_lds_dwordx4 v[98:99], off
	ds_read_b128 v[174:177], v212 offset:49152
	s_lshl_b32 s2, s10, 6
	s_cmp_le_i32 s2, s11
	s_cselect_b64 s[2:3], -1, 0
	v_cndmask_b32_e64 v98, v229, -v213, s[2:3]
	v_mov_b32_e32 v99, v98
	v_mov_b32_e32 v100, v98
	v_mov_b32_e32 v101, v98
	v_mov_b32_e32 v102, v98
	v_mov_b32_e32 v103, v98
	v_mov_b32_e32 v104, v98
	v_mov_b32_e32 v105, v98
	v_mov_b32_e32 v106, v98
	v_mov_b32_e32 v107, v98
	v_mov_b32_e32 v108, v98
	v_mov_b32_e32 v109, v98
	v_mov_b32_e32 v110, v98
	v_mov_b32_e32 v111, v98
	v_mov_b32_e32 v112, v98
	v_mov_b32_e32 v113, v98
	ds_read_b128 v[178:181], v212 offset:57344
	ds_read_b128 v[186:189], v211 offset:49152
	s_waitcnt lgkmcnt(0)
	v_mfma_f32_32x32x16_bf16 v[114:129], v[174:177], v[158:161], v[98:113]
	v_exp_f32_e32 v164, v66
	v_exp_f32_e32 v165, v82
	v_mfma_f32_32x32x16_bf16 v[98:113], v[178:181], v[158:161], v[98:113]
	ds_read_b128 v[174:177], v211 offset:57344
	v_exp_f32_e32 v166, v67
	v_exp_f32_e32 v168, v83
	v_mfma_f32_32x32x16_bf16 v[114:129], v[186:189], v[154:157], v[114:129]
	ds_read_b128 v[158:161], v210 offset:49152
	v_exp_f32_e32 v169, v68
	v_exp_f32_e32 v170, v84
	s_waitcnt lgkmcnt(0)
	v_mfma_f32_32x32x16_bf16 v[98:113], v[174:177], v[154:157], v[98:113]
	ds_read_b128 v[178:181], v210 offset:57344
	v_exp_f32_e32 v154, v69
	v_exp_f32_e32 v155, v85
	v_mfma_f32_32x32x16_bf16 v[114:129], v[158:161], v[150:153], v[114:129]
	ds_read_b128 v[66:69], v209 offset:49152
	v_exp_f32_e32 v156, v70
	v_exp_f32_e32 v157, v86
	s_waitcnt lgkmcnt(0)
	v_mfma_f32_32x32x16_bf16 v[98:113], v[178:181], v[150:153], v[98:113]
	ds_read_b128 v[82:85], v209 offset:57344
	v_exp_f32_e32 v158, v71
	v_exp_f32_e32 v159, v87
	v_mfma_f32_32x32x16_bf16 v[114:129], v[66:69], v[146:149], v[114:129]
	ds_read_b128 v[150:153], v250 offset:49152
	v_exp_f32_e32 v160, v72
	v_exp_f32_e32 v161, v88
	s_waitcnt lgkmcnt(0)
	v_mfma_f32_32x32x16_bf16 v[98:113], v[82:85], v[146:149], v[98:113]
	ds_read_b128 v[66:69], v250 offset:57344
	v_exp_f32_e32 v171, v73
	v_exp_f32_e32 v172, v89
	v_mfma_f32_32x32x16_bf16 v[114:129], v[150:153], v[142:145], v[114:129]
	ds_read_b128 v[70:73], v251 offset:49152
	v_exp_f32_e32 v146, v74
	v_exp_f32_e32 v147, v90
	s_waitcnt lgkmcnt(0)
	v_mfma_f32_32x32x16_bf16 v[98:113], v[66:69], v[142:145], v[98:113]
	ds_read_b128 v[82:85], v251 offset:57344
	v_exp_f32_e32 v148, v75
	v_exp_f32_e32 v149, v91
	v_mfma_f32_32x32x16_bf16 v[114:129], v[70:73], v[138:141], v[114:129]
	ds_read_b128 v[66:69], v252 offset:49152
	v_exp_f32_e32 v142, v76
	v_exp_f32_e32 v143, v92
	s_waitcnt lgkmcnt(0)
	v_mfma_f32_32x32x16_bf16 v[98:113], v[82:85], v[138:141], v[98:113]
	ds_read_b128 v[70:73], v252 offset:57344
	v_exp_f32_e32 v144, v77
	v_exp_f32_e32 v145, v93
	v_mfma_f32_32x32x16_bf16 v[114:129], v[66:69], v[134:137], v[114:129]
	ds_read_b128 v[74:77], v253 offset:49152
	v_exp_f32_e32 v138, v78
	v_exp_f32_e32 v139, v94
	s_waitcnt lgkmcnt(0)
	v_mfma_f32_32x32x16_bf16 v[98:113], v[70:73], v[134:137], v[98:113]
	ds_read_b128 v[66:69], v253 offset:57344
	v_exp_f32_e32 v140, v79
	v_exp_f32_e32 v141, v95
	v_mfma_f32_32x32x16_bf16 v[114:129], v[74:77], v[130:133], v[114:129]
	ds_read_b128 v[70:73], v219
	ds_read_b128 v[82:85], v200
	v_exp_f32_e32 v134, v80
	v_exp_f32_e32 v135, v96
	s_waitcnt lgkmcnt(0)
	v_mfma_f32_32x32x16_bf16 v[98:113], v[66:69], v[130:133], v[98:113]
	ds_read_b128 v[74:77], v219 offset:4096
	v_exp_f32_e32 v136, v81
	v_exp_f32_e32 v137, v97
	v_mfma_f32_32x32x16_bf16 v[114:129], v[70:73], v[82:85], v[114:129]
	ds_read_b128 v[78:81], v216
	ds_read_b128 v[86:89], v200 offset:1024
	v_cvt_pk_bf16_f32 v66, v164, v166
	v_cvt_pk_bf16_f32 v67, v169, v154
	v_cvt_pk_bf16_f32 v68, v156, v158
	v_cvt_pk_bf16_f32 v69, v160, v171
	s_nop 0
	v_permlane32_swap_b32_e32 v66, v68
	v_permlane32_swap_b32_e32 v67, v69
	s_waitcnt lgkmcnt(0)
	v_mfma_f32_32x32x16_bf16 v[98:113], v[74:77], v[82:85], v[98:113]
	ds_read_b128 v[90:93], v216 offset:4096
	v_mfma_f32_32x32x16_bf16 v[114:129], v[78:81], v[86:89], v[114:129]
	ds_read_b128 v[74:77], v217
	ds_read_b128 v[82:85], v200 offset:2048
	v_cvt_pk_bf16_f32 v70, v146, v148
	v_cvt_pk_bf16_f32 v71, v142, v144
	v_cvt_pk_bf16_f32 v72, v138, v140
	v_cvt_pk_bf16_f32 v73, v134, v136
	s_nop 0
	v_permlane32_swap_b32_e32 v70, v72
	v_permlane32_swap_b32_e32 v71, v73
	s_waitcnt lgkmcnt(0)
	v_mfma_f32_32x32x16_bf16 v[98:113], v[90:93], v[86:89], v[98:113]
	ds_read_b128 v[78:81], v217 offset:4096
	v_mfma_f32_32x32x16_bf16 v[114:129], v[74:77], v[82:85], v[114:129]
	ds_read_b128 v[86:89], v218
	ds_read_b128 v[90:93], v200 offset:3072
	v_cvt_pk_bf16_f32 v74, v165, v168
	v_cvt_pk_bf16_f32 v75, v170, v155
	v_cvt_pk_bf16_f32 v76, v157, v159
	v_cvt_pk_bf16_f32 v77, v161, v172
	s_nop 0
	v_permlane32_swap_b32_e32 v74, v76
	v_permlane32_swap_b32_e32 v75, v77
	s_waitcnt lgkmcnt(0)
	v_mfma_f32_32x32x16_bf16 v[98:113], v[78:81], v[82:85], v[98:113]
	ds_read_b128 v[94:97], v218 offset:4096
	v_mfma_f32_32x32x16_bf16 v[114:129], v[86:89], v[90:93], v[114:129]
	v_cvt_pk_bf16_f32 v82, v147, v149
	v_cvt_pk_bf16_f32 v83, v143, v145
	v_cvt_pk_bf16_f32 v84, v139, v141
	v_cvt_pk_bf16_f32 v85, v135, v137
	s_nop 0
	v_permlane32_swap_b32_e32 v82, v84
	v_permlane32_swap_b32_e32 v83, v85
	v_add_f32_e32 v78, 0, v164
	v_add_f32_e32 v78, v165, v78
	v_add_f32_e32 v78, v166, v78
	v_add_f32_e32 v78, v168, v78
	v_add_f32_e32 v78, v169, v78
	v_add_f32_e32 v78, v170, v78
	v_add_f32_e32 v78, v154, v78
	v_add_f32_e32 v78, v155, v78
	v_add_f32_e32 v78, v156, v78
	v_add_f32_e32 v78, v157, v78
	v_add_f32_e32 v78, v158, v78
	v_add_f32_e32 v78, v159, v78
	v_add_f32_e32 v78, v160, v78
	v_add_f32_e32 v78, v161, v78
	v_add_f32_e32 v78, v171, v78
	v_add_f32_e32 v78, v172, v78
	v_add_f32_e32 v78, v146, v78
	v_add_f32_e32 v78, v147, v78
	v_add_f32_e32 v78, v148, v78
	v_add_f32_e32 v78, v149, v78
	v_add_f32_e32 v78, v142, v78
	v_add_f32_e32 v78, v143, v78
	v_add_f32_e32 v78, v144, v78
	v_add_f32_e32 v78, v145, v78
	s_waitcnt lgkmcnt(0)
	v_mfma_f32_32x32x16_bf16 v[98:113], v[94:97], v[90:93], v[98:113]
	v_add_f32_e32 v78, v138, v78
	v_add_f32_e32 v78, v139, v78
	v_add_f32_e32 v78, v140, v78
	v_add_f32_e32 v78, v141, v78
	v_add_f32_e32 v78, v134, v78
	v_add_f32_e32 v78, v135, v78
	v_add_f32_e32 v78, v136, v78
	v_add_f32_e32 v78, v137, v78
	v_mov_b32_e32 v79, v78
	s_nop 1
	v_permlane32_swap_b32_e32 v78, v79
	ds_read_b64_tr_b16 v[86:87], v199 offset:0
	ds_read_b64_tr_b16 v[88:89], v199 offset:0x800
	ds_read_b64_tr_b16 v[90:91], v199 offset:0x1000
	ds_read_b64_tr_b16 v[92:93], v199 offset:0x1800
	ds_read_b64_tr_b16 v[94:95], v199 offset:0x2000
	ds_read_b64_tr_b16 v[96:97], v199 offset:0x2800
	ds_read_b64_tr_b16 v[130:131], v199 offset:0x3000
	ds_read_b64_tr_b16 v[132:133], v199 offset:0x3800
	s_waitcnt lgkmcnt(0)
	s_nop 0
	v_mfma_f32_32x32x16_bf16 v[2:17], v[66:69], v[86:89], v[2:17]
	v_max_f32_e32 v80, v115, v115
	v_max_f32_e32 v81, v114, v114
	v_max_f32_e32 v80, v81, v80
	v_max3_f32 v80, v80, v116, v117
	v_max3_f32 v80, v80, v118, v119
	v_max3_f32 v80, v80, v120, v121
	v_max3_f32 v80, v80, v122, v123
	v_mfma_f32_32x32x16_bf16 v[2:17], v[70:73], v[90:93], v[2:17]
	v_max3_f32 v80, v80, v124, v125
	v_max3_f32 v80, v80, v126, v127
	v_max3_f32 v80, v80, v128, v129
	v_max3_f32 v80, v80, v98, v99
	v_max3_f32 v80, v80, v100, v101
	v_max3_f32 v80, v80, v102, v103
	v_max3_f32 v80, v80, v104, v105
	v_mfma_f32_32x32x16_bf16 v[2:17], v[74:77], v[94:97], v[2:17]
	v_max3_f32 v80, v80, v106, v107
	v_max3_f32 v80, v80, v108, v109
	v_max3_f32 v80, v80, v110, v111
	v_max3_f32 v80, v80, v112, v113
	v_mfma_f32_32x32x16_bf16 v[2:17], v[82:85], v[130:133], v[2:17]
	ds_read_b64_tr_b16 v[86:87], v199 offset:0x200
	ds_read_b64_tr_b16 v[88:89], v199 offset:0xa00
	ds_read_b64_tr_b16 v[90:91], v199 offset:0x1200
	ds_read_b64_tr_b16 v[92:93], v199 offset:0x1a00
	ds_read_b64_tr_b16 v[94:95], v199 offset:0x2200
	ds_read_b64_tr_b16 v[96:97], v199 offset:0x2a00
	ds_read_b64_tr_b16 v[130:131], v199 offset:0x3200
	ds_read_b64_tr_b16 v[132:133], v199 offset:0x3a00
	s_waitcnt lgkmcnt(0)
	s_nop 0
	v_mfma_f32_32x32x16_bf16 v[50:65], v[66:69], v[86:89], v[50:65]
	v_mov_b32_e32 v81, v80
	s_nop 1
	v_permlane32_swap_b32_e32 v80, v81
	v_max_f32_e32 v81, v81, v81
	v_max_f32_e32 v80, v80, v80
	v_max_f32_e32 v80, v80, v81
	v_mfma_f32_32x32x16_bf16 v[50:65], v[70:73], v[90:93], v[50:65]
	v_mfma_f32_32x32x16_bf16 v[50:65], v[74:77], v[94:97], v[50:65]
	v_mfma_f32_32x32x16_bf16 v[50:65], v[82:85], v[130:133], v[50:65]
	ds_read_b64_tr_b16 v[86:87], v199 offset:0x400
	ds_read_b64_tr_b16 v[88:89], v199 offset:0xc00
	ds_read_b64_tr_b16 v[90:91], v199 offset:0x1400
	ds_read_b64_tr_b16 v[92:93], v199 offset:0x1c00
	ds_read_b64_tr_b16 v[94:95], v199 offset:0x2400
	ds_read_b64_tr_b16 v[96:97], v199 offset:0x2c00
	ds_read_b64_tr_b16 v[130:131], v199 offset:0x3400
	ds_read_b64_tr_b16 v[132:133], v199 offset:0x3c00
	s_waitcnt lgkmcnt(0)
	s_nop 0
	v_mfma_f32_32x32x16_bf16 v[34:49], v[66:69], v[86:89], v[34:49]
	v_mfma_f32_32x32x16_bf16 v[34:49], v[70:73], v[90:93], v[34:49]
	v_mfma_f32_32x32x16_bf16 v[34:49], v[74:77], v[94:97], v[34:49]
	v_mfma_f32_32x32x16_bf16 v[34:49], v[82:85], v[130:133], v[34:49]
	ds_read_b64_tr_b16 v[86:87], v199 offset:0x600
	ds_read_b64_tr_b16 v[88:89], v199 offset:0xe00
	ds_read_b64_tr_b16 v[90:91], v199 offset:0x1600
	ds_read_b64_tr_b16 v[92:93], v199 offset:0x1e00
	ds_read_b64_tr_b16 v[94:95], v199 offset:0x2600
	ds_read_b64_tr_b16 v[96:97], v199 offset:0x2e00
	ds_read_b64_tr_b16 v[130:131], v199 offset:0x3600
	ds_read_b64_tr_b16 v[132:133], v199 offset:0x3e00
	s_waitcnt lgkmcnt(0)
	s_nop 0
	v_mfma_f32_32x32x16_bf16 v[18:33], v[66:69], v[86:89], v[18:33]
	v_cmp_ge_f32_e32 vcc, s90, v80
	v_mov_b32_e32 v66, 1.0
	s_cmp_eq_u64 vcc, exec
	v_mfma_f32_32x32x16_bf16 v[18:33], v[70:73], v[90:93], v[18:33]
	v_mfma_f32_32x32x16_bf16 v[18:33], v[74:77], v[94:97], v[18:33]
	v_mfma_f32_32x32x16_bf16 v[18:33], v[82:85], v[130:133], v[18:33]
	s_cbranch_scc0 .LBB0_1358

.LBB0_1359:
	v_mov_b64_e32 v[250:251], 0x3ff
	v_mov_b64_e32 v[252:253], 0x880
	v_mov_b32_e32 v2, v0
	s_cmpk_lt_i32 s87, 0x440
	s_mov_b32 s4, 10
	v_readfirstlane_b32 s2, v2
	s_cselect_b64 s[22:23], -1, 0
	s_cmpk_gt_i32 s87, 0x43f
	s_cbranch_scc1 .LBB0_1361
	s_mul_hi_i32 s3, s87, 0x78787879
	s_lshr_b32 s5, s3, 31
	s_ashr_i32 s3, s3, 4
	s_add_i32 s62, s3, s5
	s_mul_i32 s3, s62, 0xffffffde
	s_add_i32 s3, s3, s87
	s_mul_hi_i32 s5, s3, 0x78787879
	s_lshr_b32 s6, s5, 31
	s_ashr_i32 s5, s5, 3
	s_add_i32 s33, s5, s6
	s_mul_i32 s5, s33, 0xffffffef
	s_add_i32 s94, s5, s3
	s_lshl_b32 s3, s62, 9
	s_lshl_b32 s5, s33, 8
	s_add_i32 s3, s5, s3
	s_mul_hi_i32 s15, s3, 0x500
	s_mul_i32 s14, s3, 0x500
	s_mul_i32 s3, s62, 0x1100
	s_lshl_b32 s5, s94, 8
	s_add_i32 s3, s5, s3
	s_mul_hi_i32 s19, s3, 0x500
	s_mul_i32 s18, s3, 0x500
